# AP1 + same-accumulator MFMA pairs adjacent in the in-place runs of the four sliver K-loops
# speedup vs baseline: 1.0062x; 1.0045x over previous
; #define PG8_STAGE(bufoff, gbase, voff) do { _Pragma("unroll") for (int _i = 0; _i < 2; ++_i) \
;         __builtin_amdgcn_global_load_lds((const unsigned*)((const char*)(gbase) + (size_t)_i * qstep + (voff)[0]), (PG8_LAS unsigned*)(lds + (bufoff) + ldsw + _i * 8192), 16, 0, 0); } while (0)
; #define PG8_LDA(dst, b, h) do { _Pragma("unroll") for (int m = 0; m < 4; ++m) _Pragma("unroll") for (int k = 0; k < 2; ++k) dst[m][k] = *(const PG8_LAS bf16x8*)(lds + PG8_SA(b, h) + aoff + m * 2048 + k * 1024); } while (0)
; #define PG8_LDB(dst, b, h) do { _Pragma("unroll") for (int n = 0; n < 2; ++n) _Pragma("unroll") for (int k = 0; k < 2; ++k) dst[n][k] = *(const PG8_LAS bf16x8*)(lds + PG8_SB(b, h) + boff + n * 2048 + k * 1024); } while (0)
; #define PG8_MMA(ai, bj, At, Bt) do { __builtin_amdgcn_s_setprio(1); _Pragma("unroll") for (int m = 0; m < 4; ++m) _Pragma("unroll") for (int n = 0; n < 2; ++n) _Pragma("unroll") for (int k = 0; k < 2; ++k) \
;         acc[ai][bj][m][n] = __builtin_amdgcn_mfma_f32_16x16x32_bf16(Bt[n][k], At[m][k], acc[ai][bj][m][n], 0, 0, 0); __builtin_amdgcn_s_setprio(0); } while (0)
; #define PG8_WAIT_V89() do { if constexpr (SLIVER) PG8_WAIT_V(9); else PG8_WAIT_V(8); } while (0)
; #define PG8_WAIT_L(n) asm volatile("s_waitcnt lgkmcnt(" #n ")" ::: "memory")
; #define PG8_BAR __builtin_amdgcn_s_barrier()
; #define PG8_SCHED __builtin_amdgcn_sched_barrier(0)
; template <class Epi, class Sched, bool ALIGN_EPI = false, bool SP2 = false, bool SLIVER = false>
; __device__ __forceinline__ void gemm_phase(PG8_LAS unsigned char* lds, const Gemm g, const Sched& S, const Epi& E) {
;     ...
;             const bool last = (t == nt - 2);
;             const char* a1 = cA + (size_t)(t + 1) * kstep;
;             const char* a2 = last ? nA : cA + (size_t)(t + 2) * kstep; const char* b2 = last ? nB : cB + (size_t)(t + 2) * kstep;
;             const char* a3 = a2 + kstep; const char* b3 = b2 + kstep;
;             const char* s1 = cS + (size_t)(t + 1) * kstep; const char* s2 = last ? nS : cS + (size_t)(t + 2) * kstep;
;             if (last && has_next) S.a_ready(nxt);
;             if constexpr (SP2) {
;             PG8_LDB(B0, 0, 0); PG8_LDB(B1, 0, 1); PG8_SCHED; PG8_LDA(At, 0, 0); PG8_STAGE(PG8_SA(1, 1), a1 + hstep, voffA); PG8_STAGE_S(1, s1);
;             PG8_WAIT_V89(); PG8_WAIT_L(0); PG8_BAR; PG8_MMA(0, 0, At, B0); PG8_MMA(0, 1, At, B1); PG8_BAR; PG8_SCHED;
.LBB0_498:
	s_cmp_eq_u32 s66, s80
	s_cselect_b64 s[86:87], -1, 0
	s_add_u32 s40, s16, s80
	s_addc_u32 s41, s17, s81
	s_add_u32 s68, s40, 0x100
	s_addc_u32 s69, s41, 0
	s_and_b64 s[40:41], s[86:87], exec
	s_cselect_b32 s41, s55, s69
	s_cselect_b32 s40, s54, s68
	s_add_u32 s76, s12, s80
	s_addc_u32 s77, s13, s81
	s_add_i32 s78, 0, 0x10000
	s_and_b64 s[68:69], s[86:87], exec
	v_add_u32_e32 v138, s78, v239
	s_cselect_b32 s69, s83, s77
	s_cselect_b32 s68, s82, s76
	s_add_i32 s76, 0, 0x14000
	ds_read_b128 v[146:149], v138
	ds_read_b128 v[150:153], v138 offset:1024
	ds_read_b128 v[154:157], v138 offset:2048
	ds_read_b128 v[158:161], v138 offset:3072
	v_add_u32_e32 v138, s76, v239
	ds_read_b128 v[166:169], v138
	ds_read_b128 v[170:173], v138 offset:1024
	ds_read_b128 v[174:177], v138 offset:2048
	ds_read_b128 v[162:165], v138 offset:3072
	v_lshl_add_u64 v[208:209], v[188:189], 0, s[80:81]
	v_lshl_add_u64 v[224:225], v[208:209], 0, s[34:35]
	s_add_i32 m0, s96, 0xc000
	s_mov_b64 s[88:89], 0x120080
	ds_read_b128 v[138:141], v242
	ds_read_b128 v[142:145], v242 offset:1024
	ds_read_b128 v[180:183], v242 offset:2048
	ds_read_b128 v[184:187], v242 offset:3072
	ds_read_b128 v[192:195], v242 offset:4096
	ds_read_b128 v[196:199], v242 offset:5120
	ds_read_b128 v[200:203], v242 offset:6144
	ds_read_b128 v[220:223], v242 offset:7168
	global_load_lds_dwordx4 v[224:225], off
	v_lshl_add_u64 v[208:209], v[208:209], 0, s[88:89]
	s_add_i32 m0, s96, 0xe000
	s_nop 0
	global_load_lds_dwordx4 v[208:209], off
	v_lshl_add_u64 v[208:209], v[190:191], 0, s[80:81]
	s_add_i32 m0, s94, 0x20800
	s_nop 0
	global_load_lds_dword v[208:209], off
	s_waitcnt vmcnt(9)
	s_waitcnt lgkmcnt(0)
	s_setprio 1
	s_barrier
	v_mfma_f32_16x16x32_bf16 v[134:137], v[146:149], v[138:141], v[134:137]
	v_mfma_f32_16x16x32_bf16 v[134:137], v[150:153], v[142:145], v[134:137]
	v_mfma_f32_16x16x32_bf16 v[130:133], v[154:157], v[138:141], v[130:133]
	v_mfma_f32_16x16x32_bf16 v[130:133], v[158:161], v[142:145], v[130:133]
	v_mfma_f32_16x16x32_bf16 v[126:129], v[146:149], v[180:183], v[126:129]
	v_mfma_f32_16x16x32_bf16 v[126:129], v[150:153], v[184:187], v[126:129]
	v_mfma_f32_16x16x32_bf16 v[122:125], v[154:157], v[180:183], v[122:125]
	v_mfma_f32_16x16x32_bf16 v[122:125], v[158:161], v[184:187], v[122:125]
	v_mfma_f32_16x16x32_bf16 v[118:121], v[146:149], v[192:195], v[118:121]
	v_mfma_f32_16x16x32_bf16 v[118:121], v[150:153], v[196:199], v[118:121]
	v_mfma_f32_16x16x32_bf16 v[114:117], v[154:157], v[192:195], v[114:117]
	v_mfma_f32_16x16x32_bf16 v[114:117], v[158:161], v[196:199], v[114:117]
	v_mfma_f32_16x16x32_bf16 v[110:113], v[146:149], v[200:203], v[110:113]
	v_mfma_f32_16x16x32_bf16 v[110:113], v[150:153], v[220:223], v[110:113]
	v_mfma_f32_16x16x32_bf16 v[106:109], v[154:157], v[200:203], v[106:109]
	v_mfma_f32_16x16x32_bf16 v[106:109], v[158:161], v[220:223], v[106:109]
	s_setprio 0
	s_setprio 1
	v_mfma_f32_16x16x32_bf16 v[102:105], v[166:169], v[138:141], v[102:105]
	v_mfma_f32_16x16x32_bf16 v[102:105], v[170:173], v[142:145], v[102:105]
	v_mfma_f32_16x16x32_bf16 v[98:101], v[174:177], v[138:141], v[98:101]
	v_mfma_f32_16x16x32_bf16 v[98:101], v[162:165], v[142:145], v[98:101]
	v_mfma_f32_16x16x32_bf16 v[90:93], v[166:169], v[180:183], v[90:93]
	v_mfma_f32_16x16x32_bf16 v[90:93], v[170:173], v[184:187], v[90:93]
	v_mfma_f32_16x16x32_bf16 v[86:89], v[174:177], v[180:183], v[86:89]
	v_mfma_f32_16x16x32_bf16 v[86:89], v[162:165], v[184:187], v[86:89]
	v_mfma_f32_16x16x32_bf16 v[78:81], v[166:169], v[192:195], v[78:81]
	v_mfma_f32_16x16x32_bf16 v[78:81], v[170:173], v[196:199], v[78:81]
	v_mfma_f32_16x16x32_bf16 v[74:77], v[174:177], v[192:195], v[74:77]
	v_mfma_f32_16x16x32_bf16 v[74:77], v[162:165], v[196:199], v[74:77]
	v_mfma_f32_16x16x32_bf16 v[70:73], v[166:169], v[200:203], v[70:73]
	v_mfma_f32_16x16x32_bf16 v[70:73], v[170:173], v[220:223], v[70:73]
	v_mfma_f32_16x16x32_bf16 v[66:69], v[174:177], v[200:203], v[66:69]
	v_mfma_f32_16x16x32_bf16 v[66:69], v[162:165], v[220:223], v[66:69]
	s_barrier
; #define PG8_SB(B) __builtin_amdgcn_rcpf(1.f + expneg(B))
; #define PG8_SB(B) __builtin_amdgcn_rcpf(1.f + expneg(B))
; #define PG8_STAGE(bufoff, gbase, voff) do { _Pragma("unroll") for (int _i = 0; _i < 2; ++_i) \
;         __builtin_amdgcn_global_load_lds((const unsigned*)((const char*)(gbase) + (size_t)_i * qstep + (voff)[0]), (PG8_LAS unsigned*)(lds + (bufoff) + ldsw + _i * 8192), 16, 0, 0); } while (0)
; #define PG8_LDA(dst, b, h) do { _Pragma("unroll") for (int m = 0; m < 4; ++m) _Pragma("unroll") for (int k = 0; k < 2; ++k) dst[m][k] = *(const PG8_LAS bf16x8*)(lds + PG8_SA(b, h) + aoff + m * 2048 + k * 1024); } while (0)
; #define PG8_MMA(ai, bj, At, Bt) do { __builtin_amdgcn_s_setprio(1); _Pragma("unroll") for (int m = 0; m < 4; ++m) _Pragma("unroll") for (int n = 0; n < 2; ++n) _Pragma("unroll") for (int k = 0; k < 2; ++k) \
;         acc[ai][bj][m][n] = __builtin_amdgcn_mfma_f32_16x16x32_bf16(Bt[n][k], At[m][k], acc[ai][bj][m][n], 0, 0, 0); __builtin_amdgcn_s_setprio(0); } while (0)
; #define PG8_WAIT_V89() do { if constexpr (SLIVER) PG8_WAIT_V(9); else PG8_WAIT_V(8); } while (0)
; #define PG8_LDS_S(b) do { if constexpr (SLIVER) { Sf[0] = *(const PG8_LAS bf16x8*)(lds + STAGE_BYTES + (b) * 2048 + soff0); Sf[1] = *(const PG8_LAS bf16x8*)(lds + STAGE_BYTES + (b) * 2048 + (soff0 ^ 64)); } } while (0)
; #define PG8_WAIT_L(n) asm volatile("s_waitcnt lgkmcnt(" #n ")" ::: "memory")
; #define PG8_BAR __builtin_amdgcn_s_barrier()
; #define PG8_SCHED __builtin_amdgcn_sched_barrier(0)
; template <class Epi, class Sched, bool ALIGN_EPI = false, bool SP2 = false, bool SLIVER = false>
; __device__ __forceinline__ void gemm_phase(PG8_LAS unsigned char* lds, const Gemm g, const Sched& S, const Epi& E) {
;     ...
;             PG8_LDA(At, 0, 1); PG8_LDS_S(0); PG8_STAGE(PG8_SB(0, 0), b2, voffB); PG8_STAGE(PG8_SB(0, 1), b2 + hstep, voffB); PG8_STAGE(PG8_SA(0, 0), a2, voffA);
;             PG8_WAIT_V89(); PG8_WAIT_L(0); PG8_BAR; PG8_MMA(1, 0, At, B0); PG8_MMA(1, 1, At, B1); PG8_MMA_S(); PG8_BAR; PG8_SCHED;
	s_setprio 0
	s_add_i32 s77, 0, 0x20000
	v_lshl_add_u64 v[192:193], s[68:69], 0, v[212:213]
	s_add_i32 s68, s78, s95
	v_add_u32_e32 v178, s77, v240
	v_add_u32_e32 v184, s77, v241
	s_mov_b32 m0, s68
	s_mov_b64 s[88:89], 0x60000
	ds_read_b128 v[138:141], v242 offset:16384
	ds_read_b128 v[142:145], v242 offset:17408
	ds_read_b128 v[196:199], v242 offset:18432
	ds_read_b128 v[200:203], v242 offset:19456
	ds_read_b128 v[220:223], v242 offset:20480
	ds_read_b128 v[224:227], v242 offset:21504
	ds_read_b128 v[228:231], v242 offset:22528
	ds_read_b128 v[232:235], v242 offset:23552
	ds_read_b128 v[180:183], v178
	ds_read_b128 v[184:187], v184
	global_load_lds_dwordx4 v[192:193], off
	v_lshl_add_u64 v[194:195], v[192:193], 0, s[88:89]
	s_add_i32 m0, s68, 0x2000
	s_add_i32 s68, s76, s95
	global_load_lds_dwordx4 v[194:195], off
	v_lshl_add_u64 v[194:195], v[192:193], 0, s[24:25]
	s_mov_b32 m0, s68
	s_nop 0
	global_load_lds_dwordx4 v[194:195], off
	v_lshl_add_u64 v[194:195], v[192:193], 0, s[14:15]
	s_add_i32 m0, s68, 0x2000
	s_nop 0
	global_load_lds_dwordx4 v[194:195], off
	v_lshl_add_u64 v[194:195], s[40:41], 0, v[210:211]
	s_mov_b32 m0, s96
	v_lshl_add_u64 v[208:209], v[194:195], 0, s[88:89]
	global_load_lds_dwordx4 v[194:195], off
	s_mov_b32 m0, s19
	s_nop 0
	global_load_lds_dwordx4 v[208:209], off
	s_waitcnt vmcnt(9)
	s_waitcnt lgkmcnt(0)
	s_setprio 1
	s_barrier
	v_mfma_f32_16x16x32_bf16 v[62:65], v[146:149], v[138:141], v[62:65]
	v_mfma_f32_16x16x32_bf16 v[62:65], v[150:153], v[142:145], v[62:65]
	v_mfma_f32_16x16x32_bf16 v[58:61], v[154:157], v[138:141], v[58:61]
	v_mfma_f32_16x16x32_bf16 v[58:61], v[158:161], v[142:145], v[58:61]
	v_mfma_f32_16x16x32_bf16 v[54:57], v[146:149], v[196:199], v[54:57]
	v_mfma_f32_16x16x32_bf16 v[54:57], v[150:153], v[200:203], v[54:57]
	v_mfma_f32_16x16x32_bf16 v[50:53], v[154:157], v[196:199], v[50:53]
	v_mfma_f32_16x16x32_bf16 v[50:53], v[158:161], v[200:203], v[50:53]
	v_mfma_f32_16x16x32_bf16 v[46:49], v[146:149], v[220:223], v[46:49]
	v_mfma_f32_16x16x32_bf16 v[46:49], v[150:153], v[224:227], v[46:49]
	v_mfma_f32_16x16x32_bf16 v[42:45], v[154:157], v[220:223], v[42:45]
	v_mfma_f32_16x16x32_bf16 v[42:45], v[158:161], v[224:227], v[42:45]
	v_mfma_f32_16x16x32_bf16 v[38:41], v[146:149], v[228:231], v[38:41]
	v_mfma_f32_16x16x32_bf16 v[38:41], v[150:153], v[232:235], v[38:41]
	v_mfma_f32_16x16x32_bf16 v[34:37], v[154:157], v[228:231], v[34:37]
	v_mfma_f32_16x16x32_bf16 v[34:37], v[158:161], v[232:235], v[34:37]
	s_setprio 0
	s_setprio 1
	v_mfma_f32_16x16x32_bf16 v[30:33], v[166:169], v[138:141], v[30:33]
	v_mfma_f32_16x16x32_bf16 v[30:33], v[170:173], v[142:145], v[30:33]
	v_mfma_f32_16x16x32_bf16 v[26:29], v[174:177], v[138:141], v[26:29]
	v_mfma_f32_16x16x32_bf16 v[26:29], v[162:165], v[142:145], v[26:29]
	v_mfma_f32_16x16x32_bf16 v[22:25], v[166:169], v[196:199], v[22:25]
	v_mfma_f32_16x16x32_bf16 v[22:25], v[170:173], v[200:203], v[22:25]
	v_mfma_f32_16x16x32_bf16 v[18:21], v[174:177], v[196:199], v[18:21]
	v_mfma_f32_16x16x32_bf16 v[18:21], v[162:165], v[200:203], v[18:21]
	v_mfma_f32_16x16x32_bf16 v[14:17], v[166:169], v[220:223], v[14:17]
	v_mfma_f32_16x16x32_bf16 v[14:17], v[170:173], v[224:227], v[14:17]
	v_mfma_f32_16x16x32_bf16 v[10:13], v[174:177], v[220:223], v[10:13]
	v_mfma_f32_16x16x32_bf16 v[10:13], v[162:165], v[224:227], v[10:13]
	v_mfma_f32_16x16x32_bf16 v[6:9], v[166:169], v[228:231], v[6:9]
	v_mfma_f32_16x16x32_bf16 v[6:9], v[170:173], v[232:235], v[6:9]
	v_mfma_f32_16x16x32_bf16 v[2:5], v[174:177], v[228:231], v[2:5]
	v_mfma_f32_16x16x32_bf16 v[2:5], v[162:165], v[232:235], v[2:5]
	s_setprio 0
	s_setprio 1
	s_and_b64 vcc, exec, s[52:53]
	s_cbranch_vccz .Lslv_b0
	v_mfma_f32_16x16x32_bf16 v[138:141], v[166:169], v[180:183], v[82:85]
	v_mfma_f32_16x16x32_bf16 v[142:145], v[174:177], v[180:183], v[94:97]
	v_mfma_f32_16x16x32_bf16 v[138:141], v[170:173], v[184:187], v[138:141]
	v_mfma_f32_16x16x32_bf16 v[142:145], v[162:165], v[184:187], v[142:145]
	s_branch .LBB0_502

; #define PG8_STAGE(bufoff, gbase, voff) do { _Pragma("unroll") for (int _i = 0; _i < 2; ++_i) \
;         __builtin_amdgcn_global_load_lds((const unsigned*)((const char*)(gbase) + (size_t)_i * qstep + (voff)[0]), (PG8_LAS unsigned*)(lds + (bufoff) + ldsw + _i * 8192), 16, 0, 0); } while (0)
; #define PG8_LDA(dst, b, h) do { _Pragma("unroll") for (int m = 0; m < 4; ++m) _Pragma("unroll") for (int k = 0; k < 2; ++k) dst[m][k] = *(const PG8_LAS bf16x8*)(lds + PG8_SA(b, h) + aoff + m * 2048 + k * 1024); } while (0)
; #define PG8_LDB(dst, b, h) do { _Pragma("unroll") for (int n = 0; n < 2; ++n) _Pragma("unroll") for (int k = 0; k < 2; ++k) dst[n][k] = *(const PG8_LAS bf16x8*)(lds + PG8_SB(b, h) + boff + n * 2048 + k * 1024); } while (0)
; #define PG8_MMA(ai, bj, At, Bt) do { __builtin_amdgcn_s_setprio(1); _Pragma("unroll") for (int m = 0; m < 4; ++m) _Pragma("unroll") for (int n = 0; n < 2; ++n) _Pragma("unroll") for (int k = 0; k < 2; ++k) \
;         acc[ai][bj][m][n] = __builtin_amdgcn_mfma_f32_16x16x32_bf16(Bt[n][k], At[m][k], acc[ai][bj][m][n], 0, 0, 0); __builtin_amdgcn_s_setprio(0); } while (0)
; #define PG8_WAIT_V89() do { if constexpr (SLIVER) PG8_WAIT_V(9); else PG8_WAIT_V(8); } while (0)
; #define PG8_STAGE_S(b, gbase) do { if constexpr (SLIVER) __builtin_amdgcn_global_load_lds((const unsigned*)((const char*)(gbase) + voffS), (PG8_LAS unsigned*)(lds + STAGE_BYTES + (b) * 2048 + wid * 256), 4, 0, 0); } while (0)
; #define PG8_WAIT_L(n) asm volatile("s_waitcnt lgkmcnt(" #n ")" ::: "memory")
; #define PG8_BAR __builtin_amdgcn_s_barrier()
; #define PG8_SCHED __builtin_amdgcn_sched_barrier(0)
; template <class Epi, class Sched, bool ALIGN_EPI = false, bool SP2 = false, bool SLIVER = false>
; __device__ __forceinline__ void gemm_phase(PG8_LAS unsigned char* lds, const Gemm g, const Sched& S, const Epi& E) {
;     ...
;             PG8_LDB(B0, 1, 0); PG8_LDB(B1, 1, 1); PG8_SCHED; PG8_LDA(At, 1, 0); PG8_STAGE(PG8_SA(0, 1), a2 + hstep, voffA); PG8_STAGE_S(0, s2);
;             PG8_WAIT_V89(); PG8_WAIT_L(0); PG8_BAR; PG8_MMA(0, 0, At, B0); PG8_MMA(0, 1, At, B1); PG8_BAR; PG8_SCHED;
.LBB0_502:
	s_barrier
	s_setprio 0
	s_add_u32 s68, s62, s80
	s_addc_u32 s69, s63, s81
	s_add_u32 s76, s68, 0x100
	s_addc_u32 s77, s69, 0
	s_and_b64 s[68:69], s[86:87], exec
	s_cselect_b32 s69, s85, s77
	s_cselect_b32 s68, s84, s76
	s_add_i32 s76, 0, 0x18000
	v_add_u32_e32 v82, s76, v239
	s_add_i32 s77, 0, 0x1c000
	ds_read_b128 v[146:149], v82
	ds_read_b128 v[150:153], v82 offset:1024
	ds_read_b128 v[154:157], v82 offset:2048
	ds_read_b128 v[158:161], v82 offset:3072
	v_add_u32_e32 v82, s77, v239
	ds_read_b128 v[166:169], v82
	ds_read_b128 v[170:173], v82 offset:1024
	ds_read_b128 v[174:177], v82 offset:2048
	ds_read_b128 v[162:165], v82 offset:3072
	s_mov_b32 m0, s91
	v_lshl_add_u64 v[208:209], v[194:195], 0, s[24:25]
	ds_read_b128 v[82:85], v242 offset:32768
	ds_read_b128 v[94:97], v242 offset:33792
	ds_read_b128 v[180:183], v242 offset:34816
	ds_read_b128 v[184:187], v242 offset:35840
	ds_read_b128 v[196:199], v242 offset:36864
	ds_read_b128 v[200:203], v242 offset:37888
	ds_read_b128 v[220:223], v242 offset:38912
	ds_read_b128 v[224:227], v242 offset:39936
	global_load_lds_dwordx4 v[208:209], off
	v_lshl_add_u64 v[208:209], v[194:195], 0, s[14:15]
	s_mov_b32 m0, s92
	s_nop 0
	global_load_lds_dwordx4 v[208:209], off
	v_lshl_add_u64 v[208:209], s[68:69], 0, v[214:215]
	s_mov_b32 m0, s93
	s_nop 0
	global_load_lds_dword v[208:209], off
	s_waitcnt vmcnt(9)
	s_waitcnt lgkmcnt(0)
	s_setprio 1
	s_barrier
	v_mfma_f32_16x16x32_bf16 v[134:137], v[146:149], v[82:85], v[134:137]
	v_mfma_f32_16x16x32_bf16 v[134:137], v[150:153], v[94:97], v[134:137]
	v_mfma_f32_16x16x32_bf16 v[130:133], v[154:157], v[82:85], v[130:133]
	v_mfma_f32_16x16x32_bf16 v[130:133], v[158:161], v[94:97], v[130:133]
	v_mfma_f32_16x16x32_bf16 v[126:129], v[146:149], v[180:183], v[126:129]
	v_mfma_f32_16x16x32_bf16 v[126:129], v[150:153], v[184:187], v[126:129]
	v_mfma_f32_16x16x32_bf16 v[122:125], v[154:157], v[180:183], v[122:125]
	v_mfma_f32_16x16x32_bf16 v[122:125], v[158:161], v[184:187], v[122:125]
	v_mfma_f32_16x16x32_bf16 v[118:121], v[146:149], v[196:199], v[118:121]
	v_mfma_f32_16x16x32_bf16 v[118:121], v[150:153], v[200:203], v[118:121]
	v_mfma_f32_16x16x32_bf16 v[114:117], v[154:157], v[196:199], v[114:117]
	v_mfma_f32_16x16x32_bf16 v[114:117], v[158:161], v[200:203], v[114:117]
	v_mfma_f32_16x16x32_bf16 v[110:113], v[146:149], v[220:223], v[110:113]
	v_mfma_f32_16x16x32_bf16 v[110:113], v[150:153], v[224:227], v[110:113]
	v_mfma_f32_16x16x32_bf16 v[106:109], v[154:157], v[220:223], v[106:109]
	v_mfma_f32_16x16x32_bf16 v[106:109], v[158:161], v[224:227], v[106:109]
	s_setprio 0
	s_setprio 1
	v_mfma_f32_16x16x32_bf16 v[102:105], v[166:169], v[82:85], v[102:105]
	v_mfma_f32_16x16x32_bf16 v[82:85], v[174:177], v[82:85], v[98:101]
	v_mfma_f32_16x16x32_bf16 v[98:101], v[162:165], v[94:97], v[82:85]
	v_mfma_f32_16x16x32_bf16 v[82:85], v[166:169], v[180:183], v[90:93]
	v_mfma_f32_16x16x32_bf16 v[90:93], v[170:173], v[184:187], v[82:85]
	v_mfma_f32_16x16x32_bf16 v[82:85], v[174:177], v[180:183], v[86:89]
	v_mfma_f32_16x16x32_bf16 v[78:81], v[166:169], v[196:199], v[78:81]
	v_mfma_f32_16x16x32_bf16 v[74:77], v[174:177], v[196:199], v[74:77]
	v_mfma_f32_16x16x32_bf16 v[70:73], v[166:169], v[220:223], v[70:73]
	v_mfma_f32_16x16x32_bf16 v[66:69], v[174:177], v[220:223], v[66:69]
	v_mfma_f32_16x16x32_bf16 v[102:105], v[170:173], v[94:97], v[102:105]
	v_mfma_f32_16x16x32_bf16 v[86:89], v[162:165], v[184:187], v[82:85]
	v_mfma_f32_16x16x32_bf16 v[78:81], v[170:173], v[200:203], v[78:81]
	v_mfma_f32_16x16x32_bf16 v[74:77], v[162:165], v[200:203], v[74:77]
	v_mfma_f32_16x16x32_bf16 v[70:73], v[170:173], v[224:227], v[70:73]
	v_mfma_f32_16x16x32_bf16 v[66:69], v[162:165], v[224:227], v[66:69]
	s_barrier
; #define PG8_SB(B) __builtin_amdgcn_rcpf(1.f + expneg(B))
; #define PG8_SB(B) __builtin_amdgcn_rcpf(1.f + expneg(B))
; #define PG8_STAGE(bufoff, gbase, voff) do { _Pragma("unroll") for (int _i = 0; _i < 2; ++_i) \
;         __builtin_amdgcn_global_load_lds((const unsigned*)((const char*)(gbase) + (size_t)_i * qstep + (voff)[0]), (PG8_LAS unsigned*)(lds + (bufoff) + ldsw + _i * 8192), 16, 0, 0); } while (0)
; #define PG8_LDA(dst, b, h) do { _Pragma("unroll") for (int m = 0; m < 4; ++m) _Pragma("unroll") for (int k = 0; k < 2; ++k) dst[m][k] = *(const PG8_LAS bf16x8*)(lds + PG8_SA(b, h) + aoff + m * 2048 + k * 1024); } while (0)
; #define PG8_MMA(ai, bj, At, Bt) do { __builtin_amdgcn_s_setprio(1); _Pragma("unroll") for (int m = 0; m < 4; ++m) _Pragma("unroll") for (int n = 0; n < 2; ++n) _Pragma("unroll") for (int k = 0; k < 2; ++k) \
;         acc[ai][bj][m][n] = __builtin_amdgcn_mfma_f32_16x16x32_bf16(Bt[n][k], At[m][k], acc[ai][bj][m][n], 0, 0, 0); __builtin_amdgcn_s_setprio(0); } while (0)
; #define PG8_WAIT_V89() do { if constexpr (SLIVER) PG8_WAIT_V(9); else PG8_WAIT_V(8); } while (0)
; #define PG8_LDS_S(b) do { if constexpr (SLIVER) { Sf[0] = *(const PG8_LAS bf16x8*)(lds + STAGE_BYTES + (b) * 2048 + soff0); Sf[1] = *(const PG8_LAS bf16x8*)(lds + STAGE_BYTES + (b) * 2048 + (soff0 ^ 64)); } } while (0)
; #define PG8_WAIT_L(n) asm volatile("s_waitcnt lgkmcnt(" #n ")" ::: "memory")
; #define PG8_BAR __builtin_amdgcn_s_barrier()
; #define PG8_SCHED __builtin_amdgcn_sched_barrier(0)
; template <class Epi, class Sched, bool ALIGN_EPI = false, bool SP2 = false, bool SLIVER = false>
; __device__ __forceinline__ void gemm_phase(PG8_LAS unsigned char* lds, const Gemm g, const Sched& S, const Epi& E) {
;     ...
;             PG8_LDA(At, 1, 1); PG8_LDS_S(1); PG8_STAGE(PG8_SB(1, 0), b3, voffB); PG8_STAGE(PG8_SB(1, 1), b3 + hstep, voffB); PG8_STAGE(PG8_SA(1, 0), a3, voffA);
;             PG8_WAIT_V89(); PG8_WAIT_L(0); PG8_BAR; PG8_MMA(1, 0, At, B0); PG8_MMA(1, 1, At, B1); PG8_MMA_S(); PG8_BAR; PG8_SCHED;
	s_setprio 0
	s_add_i32 s68, 0, 0x20800
	v_add_u32_e32 v178, s68, v240
	v_add_u32_e32 v184, s68, v241
	s_add_i32 s68, s76, s95
	v_lshl_add_u64 v[208:209], v[192:193], 0, s[26:27]
	s_mov_b32 m0, s68
	ds_read_b128 v[82:85], v242 offset:49152
	ds_read_b128 v[94:97], v242 offset:50176
	ds_read_b128 v[196:199], v242 offset:51200
	ds_read_b128 v[200:203], v242 offset:52224
	ds_read_b128 v[220:223], v242 offset:53248
	ds_read_b128 v[224:227], v242 offset:54272
	ds_read_b128 v[228:231], v242 offset:55296
	ds_read_b128 v[232:235], v242 offset:56320
	ds_read_b128 v[180:183], v178
	ds_read_b128 v[184:187], v184
	global_load_lds_dwordx4 v[208:209], off
	v_lshl_add_u64 v[208:209], v[192:193], 0, s[72:73]
	s_add_i32 m0, s68, 0x2000
	s_add_i32 s68, s77, s95
	global_load_lds_dwordx4 v[208:209], off
	v_lshl_add_u64 v[208:209], v[192:193], 0, s[34:35]
	s_mov_b32 m0, s68
	s_mov_b64 s[76:77], 0x120080
	global_load_lds_dwordx4 v[208:209], off
	v_lshl_add_u64 v[192:193], v[192:193], 0, s[76:77]
	s_add_i32 m0, s68, 0x2000
	s_nop 0
	global_load_lds_dwordx4 v[192:193], off
	v_lshl_add_u64 v[192:193], v[194:195], 0, s[26:27]
	s_mov_b32 m0, s97
	s_nop 0
	global_load_lds_dwordx4 v[192:193], off
	v_lshl_add_u64 v[192:193], v[194:195], 0, s[72:73]
	s_mov_b32 m0, s18
	s_nop 0
	global_load_lds_dwordx4 v[192:193], off
	s_waitcnt vmcnt(9)
	s_waitcnt lgkmcnt(0)
	s_setprio 1
	s_barrier
	v_mfma_f32_16x16x32_bf16 v[62:65], v[146:149], v[82:85], v[62:65]
	v_mfma_f32_16x16x32_bf16 v[62:65], v[150:153], v[94:97], v[62:65]
	v_mfma_f32_16x16x32_bf16 v[58:61], v[154:157], v[82:85], v[58:61]
	v_mfma_f32_16x16x32_bf16 v[58:61], v[158:161], v[94:97], v[58:61]
	v_mfma_f32_16x16x32_bf16 v[54:57], v[146:149], v[196:199], v[54:57]
	v_mfma_f32_16x16x32_bf16 v[54:57], v[150:153], v[200:203], v[54:57]
	v_mfma_f32_16x16x32_bf16 v[50:53], v[154:157], v[196:199], v[50:53]
	v_mfma_f32_16x16x32_bf16 v[50:53], v[158:161], v[200:203], v[50:53]
	v_mfma_f32_16x16x32_bf16 v[46:49], v[146:149], v[220:223], v[46:49]
	v_mfma_f32_16x16x32_bf16 v[46:49], v[150:153], v[224:227], v[46:49]
	v_mfma_f32_16x16x32_bf16 v[42:45], v[154:157], v[220:223], v[42:45]
	v_mfma_f32_16x16x32_bf16 v[42:45], v[158:161], v[224:227], v[42:45]
	v_mfma_f32_16x16x32_bf16 v[38:41], v[146:149], v[228:231], v[38:41]
	v_mfma_f32_16x16x32_bf16 v[38:41], v[150:153], v[232:235], v[38:41]
	v_mfma_f32_16x16x32_bf16 v[34:37], v[154:157], v[228:231], v[34:37]
	v_mfma_f32_16x16x32_bf16 v[34:37], v[158:161], v[232:235], v[34:37]
	s_setprio 0
	s_setprio 1
	v_mfma_f32_16x16x32_bf16 v[30:33], v[166:169], v[82:85], v[30:33]
	v_mfma_f32_16x16x32_bf16 v[30:33], v[170:173], v[94:97], v[30:33]
	v_mfma_f32_16x16x32_bf16 v[26:29], v[174:177], v[82:85], v[26:29]
	v_mfma_f32_16x16x32_bf16 v[26:29], v[162:165], v[94:97], v[26:29]
	v_mfma_f32_16x16x32_bf16 v[22:25], v[166:169], v[196:199], v[22:25]
	v_mfma_f32_16x16x32_bf16 v[22:25], v[170:173], v[200:203], v[22:25]
	v_mfma_f32_16x16x32_bf16 v[18:21], v[174:177], v[196:199], v[18:21]
	v_mfma_f32_16x16x32_bf16 v[18:21], v[162:165], v[200:203], v[18:21]
	v_mfma_f32_16x16x32_bf16 v[14:17], v[166:169], v[220:223], v[14:17]
	v_mfma_f32_16x16x32_bf16 v[14:17], v[170:173], v[224:227], v[14:17]
	v_mfma_f32_16x16x32_bf16 v[10:13], v[174:177], v[220:223], v[10:13]
	v_mfma_f32_16x16x32_bf16 v[10:13], v[162:165], v[224:227], v[10:13]
	v_mfma_f32_16x16x32_bf16 v[6:9], v[166:169], v[228:231], v[6:9]
	v_mfma_f32_16x16x32_bf16 v[6:9], v[170:173], v[232:235], v[6:9]
	v_mfma_f32_16x16x32_bf16 v[2:5], v[174:177], v[228:231], v[2:5]
	v_mfma_f32_16x16x32_bf16 v[2:5], v[162:165], v[232:235], v[2:5]
	s_setprio 0
	s_setprio 1
	s_and_b64 vcc, exec, s[52:53]
	s_cbranch_vccz .Lslv_c0
	v_mfma_f32_16x16x32_bf16 v[82:85], v[166:169], v[180:183], v[138:141]
	v_mfma_f32_16x16x32_bf16 v[94:97], v[174:177], v[180:183], v[142:145]
	v_mfma_f32_16x16x32_bf16 v[82:85], v[170:173], v[184:187], v[82:85]
	v_mfma_f32_16x16x32_bf16 v[94:97], v[162:165], v[184:187], v[94:97]
	s_branch .LBB0_497

; #define PG8_STAGE(bufoff, gbase, voff) do { _Pragma("unroll") for (int _i = 0; _i < 2; ++_i) \
;         __builtin_amdgcn_global_load_lds((const unsigned*)((const char*)(gbase) + (size_t)_i * qstep + (voff)[0]), (PG8_LAS unsigned*)(lds + (bufoff) + ldsw + _i * 8192), 16, 0, 0); } while (0)
; #define PG8_LDA(dst, b, h) do { _Pragma("unroll") for (int m = 0; m < 4; ++m) _Pragma("unroll") for (int k = 0; k < 2; ++k) dst[m][k] = *(const PG8_LAS bf16x8*)(lds + PG8_SA(b, h) + aoff + m * 2048 + k * 1024); } while (0)
; #define PG8_LDB(dst, b, h) do { _Pragma("unroll") for (int n = 0; n < 2; ++n) _Pragma("unroll") for (int k = 0; k < 2; ++k) dst[n][k] = *(const PG8_LAS bf16x8*)(lds + PG8_SB(b, h) + boff + n * 2048 + k * 1024); } while (0)
; #define PG8_MMA(ai, bj, At, Bt) do { __builtin_amdgcn_s_setprio(1); _Pragma("unroll") for (int m = 0; m < 4; ++m) _Pragma("unroll") for (int n = 0; n < 2; ++n) _Pragma("unroll") for (int k = 0; k < 2; ++k) \
;         acc[ai][bj][m][n] = __builtin_amdgcn_mfma_f32_16x16x32_bf16(Bt[n][k], At[m][k], acc[ai][bj][m][n], 0, 0, 0); __builtin_amdgcn_s_setprio(0); } while (0)
; #define PG8_WAIT_V89() do { if constexpr (SLIVER) PG8_WAIT_V(9); else PG8_WAIT_V(8); } while (0)
; #define PG8_WAIT_L(n) asm volatile("s_waitcnt lgkmcnt(" #n ")" ::: "memory")
; #define PG8_BAR __builtin_amdgcn_s_barrier()
; #define PG8_SCHED __builtin_amdgcn_sched_barrier(0)
; template <class Epi, class Sched, bool ALIGN_EPI = false, bool SP2 = false, bool SLIVER = false>
; __device__ __forceinline__ void gemm_phase(PG8_LAS unsigned char* lds, const Gemm g, const Sched& S, const Epi& E) {
;     ...
;             const bool last = (t == nt - 2);
;             const char* a1 = cA + (size_t)(t + 1) * kstep;
;             const char* a2 = last ? nA : cA + (size_t)(t + 2) * kstep; const char* b2 = last ? nB : cB + (size_t)(t + 2) * kstep;
;             const char* a3 = a2 + kstep; const char* b3 = b2 + kstep;
;             const char* s1 = cS + (size_t)(t + 1) * kstep; const char* s2 = last ? nS : cS + (size_t)(t + 2) * kstep;
;             if (last && has_next) S.a_ready(nxt);
;             if constexpr (SP2) {
;             PG8_LDB(B0, 0, 0); PG8_LDB(B1, 0, 1); PG8_SCHED; PG8_LDA(At, 0, 0); PG8_STAGE(PG8_SA(1, 1), a1 + hstep, voffA); PG8_STAGE_S(1, s1);
;             PG8_WAIT_V89(); PG8_WAIT_L(0); PG8_BAR; PG8_MMA(0, 0, At, B0); PG8_MMA(0, 1, At, B1); PG8_BAR; PG8_SCHED;
.LBB0_598:
	s_add_u32 s40, s92, s62
	s_addc_u32 s41, s93, s63
	s_add_u32 s77, s40, 0x100
	s_addc_u32 s78, s41, 0
	s_add_u32 s83, s68, s62
	s_addc_u32 s79, s69, s63
	s_add_i32 s96, 0, 0x10000
	s_cmpk_eq_i32 s62, 0xf00
	s_cselect_b64 s[80:81], -1, 0
	s_and_b64 s[40:41], s[80:81], exec
	s_cselect_b32 s41, s12, s78
	s_cselect_b32 s40, s13, s77
	v_add_u32_e32 v138, s96, v212
	s_cselect_b32 s79, s17, s79
	s_cselect_b32 s78, s55, s83
	s_add_i32 s77, 0, 0x14000
	ds_read_b128 v[146:149], v138
	ds_read_b128 v[150:153], v138 offset:1024
	ds_read_b128 v[154:157], v138 offset:2048
	ds_read_b128 v[158:161], v138 offset:3072
	v_add_u32_e32 v138, s77, v212
	ds_read_b128 v[166:169], v138
	ds_read_b128 v[170:173], v138 offset:1024
	ds_read_b128 v[174:177], v138 offset:2048
	ds_read_b128 v[162:165], v138 offset:3072
	v_lshl_add_u64 v[202:203], v[200:201], 0, s[62:63]
	v_lshl_add_u64 v[208:209], v[202:203], 0, s[30:31]
	s_add_i32 m0, s85, 0xc000
	ds_read_b128 v[138:141], v215
	ds_read_b128 v[142:145], v215 offset:1024
	ds_read_b128 v[180:183], v215 offset:2048
	ds_read_b128 v[184:187], v215 offset:3072
	ds_read_b128 v[216:219], v215 offset:4096
	ds_read_b128 v[220:223], v215 offset:5120
	ds_read_b128 v[224:227], v215 offset:6144
	ds_read_b128 v[228:231], v215 offset:7168
	global_load_lds_dwordx4 v[208:209], off
	v_lshl_add_u64 v[202:203], v[202:203], 0, s[34:35]
	s_add_i32 m0, s85, 0xe000
	s_nop 0
	global_load_lds_dwordx4 v[202:203], off
	v_lshl_add_u64 v[202:203], v[198:199], 0, s[62:63]
	s_add_i32 m0, s45, 0x20800
	s_nop 0
	global_load_lds_dword v[202:203], off
	s_waitcnt vmcnt(9)
	s_waitcnt lgkmcnt(0)
	s_setprio 1
	s_barrier
	v_mfma_f32_16x16x32_bf16 v[134:137], v[146:149], v[138:141], v[134:137]
	v_mfma_f32_16x16x32_bf16 v[134:137], v[150:153], v[142:145], v[134:137]
	v_mfma_f32_16x16x32_bf16 v[130:133], v[154:157], v[138:141], v[130:133]
	v_mfma_f32_16x16x32_bf16 v[130:133], v[158:161], v[142:145], v[130:133]
	v_mfma_f32_16x16x32_bf16 v[118:121], v[146:149], v[180:183], v[118:121]
	v_mfma_f32_16x16x32_bf16 v[118:121], v[150:153], v[184:187], v[118:121]
	v_mfma_f32_16x16x32_bf16 v[114:117], v[154:157], v[180:183], v[114:117]
	v_mfma_f32_16x16x32_bf16 v[114:117], v[158:161], v[184:187], v[114:117]
	v_mfma_f32_16x16x32_bf16 v[102:105], v[146:149], v[216:219], v[102:105]
	v_mfma_f32_16x16x32_bf16 v[102:105], v[150:153], v[220:223], v[102:105]
	v_mfma_f32_16x16x32_bf16 v[98:101], v[154:157], v[216:219], v[98:101]
	v_mfma_f32_16x16x32_bf16 v[98:101], v[158:161], v[220:223], v[98:101]
	v_mfma_f32_16x16x32_bf16 v[86:89], v[146:149], v[224:227], v[86:89]
	v_mfma_f32_16x16x32_bf16 v[86:89], v[150:153], v[228:231], v[86:89]
	v_mfma_f32_16x16x32_bf16 v[82:85], v[154:157], v[224:227], v[82:85]
	v_mfma_f32_16x16x32_bf16 v[82:85], v[158:161], v[228:231], v[82:85]
	s_setprio 0
	s_setprio 1
	v_mfma_f32_16x16x32_bf16 v[126:129], v[166:169], v[138:141], v[126:129]
	v_mfma_f32_16x16x32_bf16 v[126:129], v[170:173], v[142:145], v[126:129]
	v_mfma_f32_16x16x32_bf16 v[122:125], v[174:177], v[138:141], v[122:125]
	v_mfma_f32_16x16x32_bf16 v[122:125], v[162:165], v[142:145], v[122:125]
	v_mfma_f32_16x16x32_bf16 v[110:113], v[166:169], v[180:183], v[110:113]
	v_mfma_f32_16x16x32_bf16 v[110:113], v[170:173], v[184:187], v[110:113]
	v_mfma_f32_16x16x32_bf16 v[106:109], v[174:177], v[180:183], v[106:109]
	v_mfma_f32_16x16x32_bf16 v[106:109], v[162:165], v[184:187], v[106:109]
	v_mfma_f32_16x16x32_bf16 v[94:97], v[166:169], v[216:219], v[94:97]
	v_mfma_f32_16x16x32_bf16 v[94:97], v[170:173], v[220:223], v[94:97]
	v_mfma_f32_16x16x32_bf16 v[90:93], v[174:177], v[216:219], v[90:93]
	v_mfma_f32_16x16x32_bf16 v[90:93], v[162:165], v[220:223], v[90:93]
	v_mfma_f32_16x16x32_bf16 v[78:81], v[166:169], v[224:227], v[78:81]
	v_mfma_f32_16x16x32_bf16 v[78:81], v[170:173], v[228:231], v[78:81]
	v_mfma_f32_16x16x32_bf16 v[74:77], v[174:177], v[224:227], v[74:77]
	v_mfma_f32_16x16x32_bf16 v[74:77], v[162:165], v[228:231], v[74:77]
	s_barrier
; #define PG8_SB(B) __builtin_amdgcn_rcpf(1.f + expneg(B))
; #define PG8_SB(B) __builtin_amdgcn_rcpf(1.f + expneg(B))
; #define PG8_STAGE(bufoff, gbase, voff) do { _Pragma("unroll") for (int _i = 0; _i < 2; ++_i) \
;         __builtin_amdgcn_global_load_lds((const unsigned*)((const char*)(gbase) + (size_t)_i * qstep + (voff)[0]), (PG8_LAS unsigned*)(lds + (bufoff) + ldsw + _i * 8192), 16, 0, 0); } while (0)
; #define PG8_LDA(dst, b, h) do { _Pragma("unroll") for (int m = 0; m < 4; ++m) _Pragma("unroll") for (int k = 0; k < 2; ++k) dst[m][k] = *(const PG8_LAS bf16x8*)(lds + PG8_SA(b, h) + aoff + m * 2048 + k * 1024); } while (0)
; #define PG8_MMA(ai, bj, At, Bt) do { __builtin_amdgcn_s_setprio(1); _Pragma("unroll") for (int m = 0; m < 4; ++m) _Pragma("unroll") for (int n = 0; n < 2; ++n) _Pragma("unroll") for (int k = 0; k < 2; ++k) \
;         acc[ai][bj][m][n] = __builtin_amdgcn_mfma_f32_16x16x32_bf16(Bt[n][k], At[m][k], acc[ai][bj][m][n], 0, 0, 0); __builtin_amdgcn_s_setprio(0); } while (0)
; #define PG8_WAIT_V89() do { if constexpr (SLIVER) PG8_WAIT_V(9); else PG8_WAIT_V(8); } while (0)
; #define PG8_LDS_S(b) do { if constexpr (SLIVER) { Sf[0] = *(const PG8_LAS bf16x8*)(lds + STAGE_BYTES + (b) * 2048 + soff0); Sf[1] = *(const PG8_LAS bf16x8*)(lds + STAGE_BYTES + (b) * 2048 + (soff0 ^ 64)); } } while (0)
; #define PG8_WAIT_L(n) asm volatile("s_waitcnt lgkmcnt(" #n ")" ::: "memory")
; #define PG8_BAR __builtin_amdgcn_s_barrier()
; #define PG8_SCHED __builtin_amdgcn_sched_barrier(0)
; template <class Epi, class Sched, bool ALIGN_EPI = false, bool SP2 = false, bool SLIVER = false>
; __device__ __forceinline__ void gemm_phase(PG8_LAS unsigned char* lds, const Gemm g, const Sched& S, const Epi& E) {
;     ...
;             PG8_LDA(At, 0, 1); PG8_LDS_S(0); PG8_STAGE(PG8_SB(0, 0), b2, voffB); PG8_STAGE(PG8_SB(0, 1), b2 + hstep, voffB); PG8_STAGE(PG8_SA(0, 0), a2, voffA);
;             PG8_WAIT_V89(); PG8_WAIT_L(0); PG8_BAR; PG8_MMA(1, 0, At, B0); PG8_MMA(1, 1, At, B1); PG8_MMA_S(); PG8_BAR; PG8_SCHED;
	s_setprio 0
	s_add_i32 s83, 0, 0x20000
	v_lshl_add_u64 v[202:203], s[78:79], 0, v[190:191]
	s_add_i32 s78, s96, s18
	v_add_u32_e32 v178, s83, v213
	v_add_u32_e32 v184, s83, v214
	s_mov_b32 m0, s78
	ds_read_b128 v[138:141], v215 offset:16384
	ds_read_b128 v[142:145], v215 offset:17408
	ds_read_b128 v[216:219], v215 offset:18432
	ds_read_b128 v[220:223], v215 offset:19456
	ds_read_b128 v[224:227], v215 offset:20480
	ds_read_b128 v[228:231], v215 offset:21504
	ds_read_b128 v[232:235], v215 offset:22528
	ds_read_b128 v[240:243], v215 offset:23552
	ds_read_b128 v[180:183], v178
	ds_read_b128 v[184:187], v184
	global_load_lds_dwordx4 v[202:203], off
	v_lshl_add_u64 v[208:209], v[202:203], 0, s[20:21]
	s_add_i32 m0, s78, 0x2000
	s_add_i32 s77, s77, s18
	global_load_lds_dwordx4 v[208:209], off
	v_lshl_add_u64 v[208:209], v[202:203], 0, s[22:23]
	s_mov_b32 m0, s77
	v_lshl_add_u64 v[210:211], s[40:41], 0, v[188:189]
	global_load_lds_dwordx4 v[208:209], off
	v_lshl_add_u64 v[208:209], v[202:203], 0, s[24:25]
	s_add_i32 m0, s77, 0x2000
	s_nop 0
	global_load_lds_dwordx4 v[208:209], off
	s_mov_b32 m0, s85
	v_lshl_add_u64 v[208:209], v[210:211], 0, s[20:21]
	global_load_lds_dwordx4 v[210:211], off
	s_mov_b32 m0, s19
	s_nop 0
	global_load_lds_dwordx4 v[208:209], off
	s_waitcnt vmcnt(9)
	s_waitcnt lgkmcnt(0)
	s_setprio 1
	s_barrier
	v_mfma_f32_16x16x32_bf16 v[70:73], v[146:149], v[138:141], v[70:73]
	v_mfma_f32_16x16x32_bf16 v[70:73], v[150:153], v[142:145], v[70:73]
	v_mfma_f32_16x16x32_bf16 v[66:69], v[154:157], v[138:141], v[66:69]
	v_mfma_f32_16x16x32_bf16 v[66:69], v[158:161], v[142:145], v[66:69]
	v_mfma_f32_16x16x32_bf16 v[54:57], v[146:149], v[216:219], v[54:57]
	v_mfma_f32_16x16x32_bf16 v[54:57], v[150:153], v[220:223], v[54:57]
	v_mfma_f32_16x16x32_bf16 v[50:53], v[154:157], v[216:219], v[50:53]
	v_mfma_f32_16x16x32_bf16 v[50:53], v[158:161], v[220:223], v[50:53]
	v_mfma_f32_16x16x32_bf16 v[38:41], v[146:149], v[224:227], v[38:41]
	v_mfma_f32_16x16x32_bf16 v[38:41], v[150:153], v[228:231], v[38:41]
	v_mfma_f32_16x16x32_bf16 v[34:37], v[154:157], v[224:227], v[34:37]
	v_mfma_f32_16x16x32_bf16 v[34:37], v[158:161], v[228:231], v[34:37]
	v_mfma_f32_16x16x32_bf16 v[22:25], v[146:149], v[232:235], v[22:25]
	v_mfma_f32_16x16x32_bf16 v[22:25], v[150:153], v[240:243], v[22:25]
	v_mfma_f32_16x16x32_bf16 v[18:21], v[154:157], v[232:235], v[18:21]
	v_mfma_f32_16x16x32_bf16 v[18:21], v[158:161], v[240:243], v[18:21]
	s_setprio 0
	s_setprio 1
	v_mfma_f32_16x16x32_bf16 v[62:65], v[166:169], v[138:141], v[62:65]
	v_mfma_f32_16x16x32_bf16 v[62:65], v[170:173], v[142:145], v[62:65]
	v_mfma_f32_16x16x32_bf16 v[58:61], v[174:177], v[138:141], v[58:61]
	v_mfma_f32_16x16x32_bf16 v[58:61], v[162:165], v[142:145], v[58:61]
	v_mfma_f32_16x16x32_bf16 v[46:49], v[166:169], v[216:219], v[46:49]
	v_mfma_f32_16x16x32_bf16 v[46:49], v[170:173], v[220:223], v[46:49]
	v_mfma_f32_16x16x32_bf16 v[42:45], v[174:177], v[216:219], v[42:45]
	v_mfma_f32_16x16x32_bf16 v[42:45], v[162:165], v[220:223], v[42:45]
	v_mfma_f32_16x16x32_bf16 v[30:33], v[166:169], v[224:227], v[30:33]
	v_mfma_f32_16x16x32_bf16 v[30:33], v[170:173], v[228:231], v[30:33]
	v_mfma_f32_16x16x32_bf16 v[26:29], v[174:177], v[224:227], v[26:29]
	v_mfma_f32_16x16x32_bf16 v[26:29], v[162:165], v[228:231], v[26:29]
	v_mfma_f32_16x16x32_bf16 v[14:17], v[166:169], v[232:235], v[14:17]
	v_mfma_f32_16x16x32_bf16 v[14:17], v[170:173], v[240:243], v[14:17]
	v_mfma_f32_16x16x32_bf16 v[10:13], v[174:177], v[232:235], v[10:13]
	v_mfma_f32_16x16x32_bf16 v[10:13], v[162:165], v[240:243], v[10:13]
	s_setprio 0
	s_setprio 1
	s_and_b64 vcc, exec, s[52:53]
	s_cbranch_vccz .Lslv_b1
	v_mfma_f32_16x16x32_bf16 v[138:141], v[166:169], v[180:183], v[6:9]
	v_mfma_f32_16x16x32_bf16 v[142:145], v[174:177], v[180:183], v[2:5]
	v_mfma_f32_16x16x32_bf16 v[138:141], v[170:173], v[184:187], v[138:141]
	v_mfma_f32_16x16x32_bf16 v[142:145], v[162:165], v[184:187], v[142:145]
	s_branch .LBB0_602

; #define PG8_STAGE(bufoff, gbase, voff) do { _Pragma("unroll") for (int _i = 0; _i < 2; ++_i) \
;         __builtin_amdgcn_global_load_lds((const unsigned*)((const char*)(gbase) + (size_t)_i * qstep + (voff)[0]), (PG8_LAS unsigned*)(lds + (bufoff) + ldsw + _i * 8192), 16, 0, 0); } while (0)
; #define PG8_LDA(dst, b, h) do { _Pragma("unroll") for (int m = 0; m < 4; ++m) _Pragma("unroll") for (int k = 0; k < 2; ++k) dst[m][k] = *(const PG8_LAS bf16x8*)(lds + PG8_SA(b, h) + aoff + m * 2048 + k * 1024); } while (0)
; #define PG8_LDB(dst, b, h) do { _Pragma("unroll") for (int n = 0; n < 2; ++n) _Pragma("unroll") for (int k = 0; k < 2; ++k) dst[n][k] = *(const PG8_LAS bf16x8*)(lds + PG8_SB(b, h) + boff + n * 2048 + k * 1024); } while (0)
; #define PG8_MMA(ai, bj, At, Bt) do { __builtin_amdgcn_s_setprio(1); _Pragma("unroll") for (int m = 0; m < 4; ++m) _Pragma("unroll") for (int n = 0; n < 2; ++n) _Pragma("unroll") for (int k = 0; k < 2; ++k) \
;         acc[ai][bj][m][n] = __builtin_amdgcn_mfma_f32_16x16x32_bf16(Bt[n][k], At[m][k], acc[ai][bj][m][n], 0, 0, 0); __builtin_amdgcn_s_setprio(0); } while (0)
; #define PG8_WAIT_V89() do { if constexpr (SLIVER) PG8_WAIT_V(9); else PG8_WAIT_V(8); } while (0)
; #define PG8_STAGE_S(b, gbase) do { if constexpr (SLIVER) __builtin_amdgcn_global_load_lds((const unsigned*)((const char*)(gbase) + voffS), (PG8_LAS unsigned*)(lds + STAGE_BYTES + (b) * 2048 + wid * 256), 4, 0, 0); } while (0)
; #define PG8_WAIT_L(n) asm volatile("s_waitcnt lgkmcnt(" #n ")" ::: "memory")
; #define PG8_BAR __builtin_amdgcn_s_barrier()
; #define PG8_SCHED __builtin_amdgcn_sched_barrier(0)
; template <class Epi, class Sched, bool ALIGN_EPI = false, bool SP2 = false, bool SLIVER = false>
; __device__ __forceinline__ void gemm_phase(PG8_LAS unsigned char* lds, const Gemm g, const Sched& S, const Epi& E) {
;     ...
;             PG8_LDB(B0, 1, 0); PG8_LDB(B1, 1, 1); PG8_SCHED; PG8_LDA(At, 1, 0); PG8_STAGE(PG8_SA(0, 1), a2 + hstep, voffA); PG8_STAGE_S(0, s2);
;             PG8_WAIT_V89(); PG8_WAIT_L(0); PG8_BAR; PG8_MMA(0, 0, At, B0); PG8_MMA(0, 1, At, B1); PG8_BAR; PG8_SCHED;
.LBB0_602:
	s_barrier
	s_setprio 0
	s_add_u32 s77, s94, s62
	s_addc_u32 s78, s95, s63
	s_add_u32 s77, s77, 0x100
	s_addc_u32 s83, s78, 0
	s_and_b64 s[78:79], s[80:81], exec
	s_cselect_b32 s79, s66, s83
	s_cselect_b32 s78, s67, s77
	s_add_i32 s77, 0, 0x18000
	v_add_u32_e32 v2, s77, v212
	s_add_i32 s80, 0, 0x1c000
	ds_read_b128 v[146:149], v2
	ds_read_b128 v[150:153], v2 offset:1024
	ds_read_b128 v[154:157], v2 offset:2048
	ds_read_b128 v[158:161], v2 offset:3072
	v_add_u32_e32 v2, s80, v212
	ds_read_b128 v[166:169], v2
	ds_read_b128 v[170:173], v2 offset:1024
	ds_read_b128 v[174:177], v2 offset:2048
	ds_read_b128 v[162:165], v2 offset:3072
	s_mov_b32 m0, s49
	v_lshl_add_u64 v[208:209], v[210:211], 0, s[22:23]
	ds_read_b128 v[2:5], v215 offset:32768
	ds_read_b128 v[6:9], v215 offset:33792
	ds_read_b128 v[180:183], v215 offset:34816
	ds_read_b128 v[184:187], v215 offset:35840
	ds_read_b128 v[216:219], v215 offset:36864
	ds_read_b128 v[220:223], v215 offset:37888
	ds_read_b128 v[224:227], v215 offset:38912
	ds_read_b128 v[228:231], v215 offset:39936
	global_load_lds_dwordx4 v[208:209], off
	v_lshl_add_u64 v[208:209], v[210:211], 0, s[24:25]
	s_mov_b32 m0, s50
	s_nop 0
	global_load_lds_dwordx4 v[208:209], off
	v_lshl_add_u64 v[208:209], s[78:79], 0, v[192:193]
	s_mov_b32 m0, s51
	s_nop 0
	global_load_lds_dword v[208:209], off
	s_waitcnt vmcnt(9)
	s_waitcnt lgkmcnt(0)
	s_setprio 1
	s_barrier
	v_mfma_f32_16x16x32_bf16 v[134:137], v[146:149], v[2:5], v[134:137]
	v_mfma_f32_16x16x32_bf16 v[134:137], v[150:153], v[6:9], v[134:137]
	v_mfma_f32_16x16x32_bf16 v[130:133], v[154:157], v[2:5], v[130:133]
	v_mfma_f32_16x16x32_bf16 v[130:133], v[158:161], v[6:9], v[130:133]
	v_mfma_f32_16x16x32_bf16 v[118:121], v[146:149], v[180:183], v[118:121]
	v_mfma_f32_16x16x32_bf16 v[118:121], v[150:153], v[184:187], v[118:121]
	v_mfma_f32_16x16x32_bf16 v[114:117], v[154:157], v[180:183], v[114:117]
	v_mfma_f32_16x16x32_bf16 v[114:117], v[158:161], v[184:187], v[114:117]
	v_mfma_f32_16x16x32_bf16 v[102:105], v[146:149], v[216:219], v[102:105]
	v_mfma_f32_16x16x32_bf16 v[102:105], v[150:153], v[220:223], v[102:105]
	v_mfma_f32_16x16x32_bf16 v[98:101], v[154:157], v[216:219], v[98:101]
	v_mfma_f32_16x16x32_bf16 v[98:101], v[158:161], v[220:223], v[98:101]
	v_mfma_f32_16x16x32_bf16 v[86:89], v[146:149], v[224:227], v[86:89]
	v_mfma_f32_16x16x32_bf16 v[86:89], v[150:153], v[228:231], v[86:89]
	v_mfma_f32_16x16x32_bf16 v[82:85], v[154:157], v[224:227], v[82:85]
	v_mfma_f32_16x16x32_bf16 v[82:85], v[158:161], v[228:231], v[82:85]
	s_setprio 0
	s_setprio 1
	v_mfma_f32_16x16x32_bf16 v[126:129], v[166:169], v[2:5], v[126:129]
	v_mfma_f32_16x16x32_bf16 v[2:5], v[174:177], v[2:5], v[122:125]
	v_mfma_f32_16x16x32_bf16 v[122:125], v[162:165], v[6:9], v[2:5]
	v_mfma_f32_16x16x32_bf16 v[2:5], v[166:169], v[180:183], v[110:113]
	v_mfma_f32_16x16x32_bf16 v[110:113], v[170:173], v[184:187], v[2:5]
	v_mfma_f32_16x16x32_bf16 v[2:5], v[174:177], v[180:183], v[106:109]
	v_mfma_f32_16x16x32_bf16 v[106:109], v[162:165], v[184:187], v[2:5]
	v_mfma_f32_16x16x32_bf16 v[2:5], v[166:169], v[216:219], v[94:97]
	v_mfma_f32_16x16x32_bf16 v[94:97], v[170:173], v[220:223], v[2:5]
	v_mfma_f32_16x16x32_bf16 v[2:5], v[174:177], v[216:219], v[90:93]
	v_mfma_f32_16x16x32_bf16 v[90:93], v[162:165], v[220:223], v[2:5]
	v_mfma_f32_16x16x32_bf16 v[2:5], v[166:169], v[224:227], v[78:81]
	v_mfma_f32_16x16x32_bf16 v[78:81], v[170:173], v[228:231], v[2:5]
	v_mfma_f32_16x16x32_bf16 v[2:5], v[174:177], v[224:227], v[74:77]
	v_mfma_f32_16x16x32_bf16 v[126:129], v[170:173], v[6:9], v[126:129]
	v_mfma_f32_16x16x32_bf16 v[74:77], v[162:165], v[228:231], v[2:5]
	s_barrier
; #define PG8_SB(B) __builtin_amdgcn_rcpf(1.f + expneg(B))
; #define PG8_SB(B) __builtin_amdgcn_rcpf(1.f + expneg(B))
; #define PG8_STAGE(bufoff, gbase, voff) do { _Pragma("unroll") for (int _i = 0; _i < 2; ++_i) \
;         __builtin_amdgcn_global_load_lds((const unsigned*)((const char*)(gbase) + (size_t)_i * qstep + (voff)[0]), (PG8_LAS unsigned*)(lds + (bufoff) + ldsw + _i * 8192), 16, 0, 0); } while (0)
; #define PG8_LDA(dst, b, h) do { _Pragma("unroll") for (int m = 0; m < 4; ++m) _Pragma("unroll") for (int k = 0; k < 2; ++k) dst[m][k] = *(const PG8_LAS bf16x8*)(lds + PG8_SA(b, h) + aoff + m * 2048 + k * 1024); } while (0)
; #define PG8_MMA(ai, bj, At, Bt) do { __builtin_amdgcn_s_setprio(1); _Pragma("unroll") for (int m = 0; m < 4; ++m) _Pragma("unroll") for (int n = 0; n < 2; ++n) _Pragma("unroll") for (int k = 0; k < 2; ++k) \
;         acc[ai][bj][m][n] = __builtin_amdgcn_mfma_f32_16x16x32_bf16(Bt[n][k], At[m][k], acc[ai][bj][m][n], 0, 0, 0); __builtin_amdgcn_s_setprio(0); } while (0)
; #define PG8_WAIT_V89() do { if constexpr (SLIVER) PG8_WAIT_V(9); else PG8_WAIT_V(8); } while (0)
; #define PG8_LDS_S(b) do { if constexpr (SLIVER) { Sf[0] = *(const PG8_LAS bf16x8*)(lds + STAGE_BYTES + (b) * 2048 + soff0); Sf[1] = *(const PG8_LAS bf16x8*)(lds + STAGE_BYTES + (b) * 2048 + (soff0 ^ 64)); } } while (0)
; #define PG8_WAIT_L(n) asm volatile("s_waitcnt lgkmcnt(" #n ")" ::: "memory")
; #define PG8_BAR __builtin_amdgcn_s_barrier()
; #define PG8_SCHED __builtin_amdgcn_sched_barrier(0)
; template <class Epi, class Sched, bool ALIGN_EPI = false, bool SP2 = false, bool SLIVER = false>
; __device__ __forceinline__ void gemm_phase(PG8_LAS unsigned char* lds, const Gemm g, const Sched& S, const Epi& E) {
;     ...
;             PG8_LDA(At, 1, 1); PG8_LDS_S(1); PG8_STAGE(PG8_SB(1, 0), b3, voffB); PG8_STAGE(PG8_SB(1, 1), b3 + hstep, voffB); PG8_STAGE(PG8_SA(1, 0), a3, voffA);
;             PG8_WAIT_V89(); PG8_WAIT_L(0); PG8_BAR; PG8_MMA(1, 0, At, B0); PG8_MMA(1, 1, At, B1); PG8_MMA_S(); PG8_BAR; PG8_SCHED;
	s_setprio 0
	s_add_i32 s78, 0, 0x20800
	s_add_i32 s77, s77, s18
	v_add_u32_e32 v178, s78, v213
	v_add_u32_e32 v184, s78, v214
	v_lshl_add_u64 v[208:209], v[202:203], 0, s[26:27]
	s_mov_b32 m0, s77
	ds_read_b128 v[2:5], v215 offset:49152
	ds_read_b128 v[6:9], v215 offset:50176
	ds_read_b128 v[216:219], v215 offset:51200
	ds_read_b128 v[220:223], v215 offset:52224
	ds_read_b128 v[224:227], v215 offset:53248
	ds_read_b128 v[228:231], v215 offset:54272
	ds_read_b128 v[232:235], v215 offset:55296
	ds_read_b128 v[240:243], v215 offset:56320
	ds_read_b128 v[180:183], v178
	ds_read_b128 v[184:187], v184
	global_load_lds_dwordx4 v[208:209], off
	v_lshl_add_u64 v[208:209], v[202:203], 0, s[28:29]
	s_add_i32 m0, s77, 0x2000
	s_add_i32 s77, s80, s18
	global_load_lds_dwordx4 v[208:209], off
	v_lshl_add_u64 v[208:209], v[202:203], 0, s[30:31]
	s_mov_b32 m0, s77
	v_lshl_add_u64 v[202:203], v[202:203], 0, s[34:35]
	global_load_lds_dwordx4 v[208:209], off
	s_add_i32 m0, s77, 0x2000
	s_nop 0
	global_load_lds_dwordx4 v[202:203], off
	v_lshl_add_u64 v[202:203], v[210:211], 0, s[26:27]
	s_mov_b32 m0, s10
	s_nop 0
	global_load_lds_dwordx4 v[202:203], off
	v_lshl_add_u64 v[202:203], v[210:211], 0, s[28:29]
	s_mov_b32 m0, s2
	s_nop 0
	global_load_lds_dwordx4 v[202:203], off
	s_waitcnt vmcnt(9)
	s_waitcnt lgkmcnt(0)
	s_setprio 1
	s_barrier
	v_mfma_f32_16x16x32_bf16 v[70:73], v[146:149], v[2:5], v[70:73]
	v_mfma_f32_16x16x32_bf16 v[70:73], v[150:153], v[6:9], v[70:73]
	v_mfma_f32_16x16x32_bf16 v[66:69], v[154:157], v[2:5], v[66:69]
	v_mfma_f32_16x16x32_bf16 v[66:69], v[158:161], v[6:9], v[66:69]
	v_mfma_f32_16x16x32_bf16 v[54:57], v[146:149], v[216:219], v[54:57]
	v_mfma_f32_16x16x32_bf16 v[54:57], v[150:153], v[220:223], v[54:57]
	v_mfma_f32_16x16x32_bf16 v[50:53], v[154:157], v[216:219], v[50:53]
	v_mfma_f32_16x16x32_bf16 v[50:53], v[158:161], v[220:223], v[50:53]
	v_mfma_f32_16x16x32_bf16 v[38:41], v[146:149], v[224:227], v[38:41]
	v_mfma_f32_16x16x32_bf16 v[38:41], v[150:153], v[228:231], v[38:41]
	v_mfma_f32_16x16x32_bf16 v[34:37], v[154:157], v[224:227], v[34:37]
	v_mfma_f32_16x16x32_bf16 v[34:37], v[158:161], v[228:231], v[34:37]
	v_mfma_f32_16x16x32_bf16 v[22:25], v[146:149], v[232:235], v[22:25]
	v_mfma_f32_16x16x32_bf16 v[22:25], v[150:153], v[240:243], v[22:25]
	v_mfma_f32_16x16x32_bf16 v[18:21], v[154:157], v[232:235], v[18:21]
	v_mfma_f32_16x16x32_bf16 v[18:21], v[158:161], v[240:243], v[18:21]
	s_setprio 0
	s_setprio 1
	v_mfma_f32_16x16x32_bf16 v[62:65], v[166:169], v[2:5], v[62:65]
	v_mfma_f32_16x16x32_bf16 v[2:5], v[174:177], v[2:5], v[58:61]
	v_mfma_f32_16x16x32_bf16 v[58:61], v[162:165], v[6:9], v[2:5]
	v_mfma_f32_16x16x32_bf16 v[2:5], v[166:169], v[216:219], v[46:49]
	v_mfma_f32_16x16x32_bf16 v[46:49], v[170:173], v[220:223], v[2:5]
	v_mfma_f32_16x16x32_bf16 v[2:5], v[174:177], v[216:219], v[42:45]
	v_mfma_f32_16x16x32_bf16 v[42:45], v[162:165], v[220:223], v[2:5]
	v_mfma_f32_16x16x32_bf16 v[2:5], v[166:169], v[224:227], v[30:33]
	v_mfma_f32_16x16x32_bf16 v[30:33], v[170:173], v[228:231], v[2:5]
	v_mfma_f32_16x16x32_bf16 v[2:5], v[174:177], v[224:227], v[26:29]
	v_mfma_f32_16x16x32_bf16 v[26:29], v[162:165], v[228:231], v[2:5]
	v_mfma_f32_16x16x32_bf16 v[2:5], v[166:169], v[232:235], v[14:17]
	v_mfma_f32_16x16x32_bf16 v[14:17], v[170:173], v[240:243], v[2:5]
	v_mfma_f32_16x16x32_bf16 v[2:5], v[174:177], v[232:235], v[10:13]
	v_mfma_f32_16x16x32_bf16 v[62:65], v[170:173], v[6:9], v[62:65]
	v_mfma_f32_16x16x32_bf16 v[10:13], v[162:165], v[240:243], v[2:5]
	s_setprio 0
	s_setprio 1
	s_and_b64 vcc, exec, s[52:53]
	s_cbranch_vccz .Lslv_c1
	v_mfma_f32_16x16x32_bf16 v[2:5], v[166:169], v[180:183], v[138:141]
	v_mfma_f32_16x16x32_bf16 v[6:9], v[170:173], v[184:187], v[2:5]
	v_mfma_f32_16x16x32_bf16 v[2:5], v[174:177], v[180:183], v[142:145]
	v_mfma_f32_16x16x32_bf16 v[2:5], v[162:165], v[184:187], v[2:5]
	s_branch .LBB0_597

; #define PG8_STAGE(bufoff, gbase, voff) do { _Pragma("unroll") for (int _i = 0; _i < 2; ++_i) \
;         __builtin_amdgcn_global_load_lds((const unsigned*)((const char*)(gbase) + (size_t)_i * qstep + (voff)[0]), (PG8_LAS unsigned*)(lds + (bufoff) + ldsw + _i * 8192), 16, 0, 0); } while (0)
; #define PG8_LDA(dst, b, h) do { _Pragma("unroll") for (int m = 0; m < 4; ++m) _Pragma("unroll") for (int k = 0; k < 2; ++k) dst[m][k] = *(const PG8_LAS bf16x8*)(lds + PG8_SA(b, h) + aoff + m * 2048 + k * 1024); } while (0)
; #define PG8_LDB(dst, b, h) do { _Pragma("unroll") for (int n = 0; n < 2; ++n) _Pragma("unroll") for (int k = 0; k < 2; ++k) dst[n][k] = *(const PG8_LAS bf16x8*)(lds + PG8_SB(b, h) + boff + n * 2048 + k * 1024); } while (0)
; #define PG8_MMA(ai, bj, At, Bt) do { __builtin_amdgcn_s_setprio(1); _Pragma("unroll") for (int m = 0; m < 4; ++m) _Pragma("unroll") for (int n = 0; n < 2; ++n) _Pragma("unroll") for (int k = 0; k < 2; ++k) \
;         acc[ai][bj][m][n] = __builtin_amdgcn_mfma_f32_16x16x32_bf16(Bt[n][k], At[m][k], acc[ai][bj][m][n], 0, 0, 0); __builtin_amdgcn_s_setprio(0); } while (0)
; #define PG8_WAIT_V89() do { if constexpr (SLIVER) PG8_WAIT_V(9); else PG8_WAIT_V(8); } while (0)
; #define PG8_WAIT_L(n) asm volatile("s_waitcnt lgkmcnt(" #n ")" ::: "memory")
; #define PG8_BAR __builtin_amdgcn_s_barrier()
; #define PG8_SCHED __builtin_amdgcn_sched_barrier(0)
; template <class Epi, class Sched, bool ALIGN_EPI = false, bool SP2 = false, bool SLIVER = false>
; __device__ __forceinline__ void gemm_phase(PG8_LAS unsigned char* lds, const Gemm g, const Sched& S, const Epi& E) {
;     ...
;             const bool last = (t == nt - 2);
;             const char* a1 = cA + (size_t)(t + 1) * kstep;
;             const char* a2 = last ? nA : cA + (size_t)(t + 2) * kstep; const char* b2 = last ? nB : cB + (size_t)(t + 2) * kstep;
;             const char* a3 = a2 + kstep; const char* b3 = b2 + kstep;
;             const char* s1 = cS + (size_t)(t + 1) * kstep; const char* s2 = last ? nS : cS + (size_t)(t + 2) * kstep;
;             if (last && has_next) S.a_ready(nxt);
;             if constexpr (SP2) {
;             PG8_LDB(B0, 0, 0); PG8_LDB(B1, 0, 1); PG8_SCHED; PG8_LDA(At, 0, 0); PG8_STAGE(PG8_SA(1, 1), a1 + hstep, voffA); PG8_STAGE_S(1, s1);
;             PG8_WAIT_V89(); PG8_WAIT_L(0); PG8_BAR; PG8_MMA(0, 0, At, B0); PG8_MMA(0, 1, At, B1); PG8_BAR; PG8_SCHED;
.LBB0_811:
	s_add_u32 s13, s90, s62
	s_addc_u32 s40, s91, s63
	s_add_u32 s13, s13, 0x100
	s_addc_u32 s66, s40, 0
	s_add_u32 s68, s2, s62
	s_addc_u32 s67, s3, s63
	s_add_i32 s69, 0, 0x10000
	s_cmpk_eq_i32 s62, 0x2b00
	s_cselect_b64 s[80:81], -1, 0
	s_and_b64 s[40:41], s[80:81], exec
	s_cselect_b32 s41, s85, s66
	s_cselect_b32 s40, s84, s13
	v_add_u32_e32 v66, s69, v220
	s_cselect_b32 s67, s87, s67
	s_cselect_b32 s66, s86, s68
	s_add_i32 s13, 0, 0x14000
	ds_read_b128 v[154:157], v66
	ds_read_b128 v[158:161], v66 offset:1024
	ds_read_b128 v[162:165], v66 offset:2048
	ds_read_b128 v[174:177], v66 offset:3072
	v_add_u32_e32 v66, s13, v220
	ds_read_b128 v[184:187], v66
	ds_read_b128 v[188:191], v66 offset:1024
	ds_read_b128 v[192:195], v66 offset:2048
	ds_read_b128 v[180:183], v66 offset:3072
	v_lshl_add_u64 v[146:147], v[214:215], 0, s[62:63]
	v_lshl_add_u64 v[148:149], v[146:147], 0, s[8:9]
	s_add_i32 m0, s19, 0xc000
	s_mov_b64 s[94:95], 0x210080
	ds_read_b128 v[66:69], v223
	ds_read_b128 v[70:73], v223 offset:1024
	ds_read_b128 v[74:77], v223 offset:2048
	ds_read_b128 v[78:81], v223 offset:3072
	ds_read_b128 v[216:219], v223 offset:4096
	ds_read_b128 v[224:227], v223 offset:5120
	ds_read_b128 v[228:231], v223 offset:6144
	ds_read_b128 v[232:235], v223 offset:7168
	global_load_lds_dwordx4 v[148:149], off
	v_lshl_add_u64 v[146:147], v[146:147], 0, s[94:95]
	s_add_i32 m0, s19, 0xe000
	s_nop 0
	global_load_lds_dwordx4 v[146:147], off
	v_lshl_add_u64 v[146:147], v[212:213], 0, s[62:63]
	s_add_i32 m0, s96, 0x20800
	s_nop 0
	global_load_lds_dword v[146:147], off
	s_waitcnt vmcnt(9)
	s_waitcnt lgkmcnt(0)
	s_setprio 1
	s_barrier
	v_mfma_f32_16x16x32_bf16 v[146:149], v[154:157], v[66:69], v[170:173]
	v_mfma_f32_16x16x32_bf16 v[150:153], v[162:165], v[66:69], v[166:169]
	v_mfma_f32_16x16x32_bf16 v[134:137], v[154:157], v[74:77], v[134:137]
	v_mfma_f32_16x16x32_bf16 v[130:133], v[162:165], v[74:77], v[130:133]
	v_mfma_f32_16x16x32_bf16 v[118:121], v[154:157], v[216:219], v[118:121]
	v_mfma_f32_16x16x32_bf16 v[114:117], v[162:165], v[216:219], v[114:117]
	v_mfma_f32_16x16x32_bf16 v[102:105], v[154:157], v[228:231], v[102:105]
	v_mfma_f32_16x16x32_bf16 v[98:101], v[162:165], v[228:231], v[98:101]
	v_mfma_f32_16x16x32_bf16 v[146:149], v[158:161], v[70:73], v[146:149]
	v_mfma_f32_16x16x32_bf16 v[150:153], v[174:177], v[70:73], v[150:153]
	v_mfma_f32_16x16x32_bf16 v[134:137], v[158:161], v[78:81], v[134:137]
	v_mfma_f32_16x16x32_bf16 v[130:133], v[174:177], v[78:81], v[130:133]
	v_mfma_f32_16x16x32_bf16 v[118:121], v[158:161], v[224:227], v[118:121]
	v_mfma_f32_16x16x32_bf16 v[114:117], v[174:177], v[224:227], v[114:117]
	v_mfma_f32_16x16x32_bf16 v[102:105], v[158:161], v[232:235], v[102:105]
	v_mfma_f32_16x16x32_bf16 v[98:101], v[174:177], v[232:235], v[98:101]
	s_setprio 0
	s_setprio 1
	v_mfma_f32_16x16x32_bf16 v[142:145], v[184:187], v[66:69], v[142:145]
	v_mfma_f32_16x16x32_bf16 v[66:69], v[192:195], v[66:69], v[138:141]
	v_mfma_f32_16x16x32_bf16 v[138:141], v[180:183], v[70:73], v[66:69]
	v_mfma_f32_16x16x32_bf16 v[66:69], v[184:187], v[74:77], v[126:129]
	v_mfma_f32_16x16x32_bf16 v[126:129], v[188:191], v[78:81], v[66:69]
	v_mfma_f32_16x16x32_bf16 v[66:69], v[192:195], v[74:77], v[122:125]
	v_mfma_f32_16x16x32_bf16 v[122:125], v[180:183], v[78:81], v[66:69]
	v_mfma_f32_16x16x32_bf16 v[66:69], v[184:187], v[216:219], v[110:113]
	v_mfma_f32_16x16x32_bf16 v[110:113], v[188:191], v[224:227], v[66:69]
	v_mfma_f32_16x16x32_bf16 v[66:69], v[192:195], v[216:219], v[106:109]
	v_mfma_f32_16x16x32_bf16 v[106:109], v[180:183], v[224:227], v[66:69]
	v_mfma_f32_16x16x32_bf16 v[66:69], v[184:187], v[228:231], v[94:97]
	v_mfma_f32_16x16x32_bf16 v[94:97], v[188:191], v[232:235], v[66:69]
	v_mfma_f32_16x16x32_bf16 v[66:69], v[192:195], v[228:231], v[90:93]
	v_mfma_f32_16x16x32_bf16 v[142:145], v[188:191], v[70:73], v[142:145]
	v_mfma_f32_16x16x32_bf16 v[90:93], v[180:183], v[232:235], v[66:69]
	s_barrier
; #define PG8_SB(B) __builtin_amdgcn_rcpf(1.f + expneg(B))
; #define PG8_SB(B) __builtin_amdgcn_rcpf(1.f + expneg(B))
; #define PG8_STAGE(bufoff, gbase, voff) do { _Pragma("unroll") for (int _i = 0; _i < 2; ++_i) \
;         __builtin_amdgcn_global_load_lds((const unsigned*)((const char*)(gbase) + (size_t)_i * qstep + (voff)[0]), (PG8_LAS unsigned*)(lds + (bufoff) + ldsw + _i * 8192), 16, 0, 0); } while (0)
; #define PG8_LDA(dst, b, h) do { _Pragma("unroll") for (int m = 0; m < 4; ++m) _Pragma("unroll") for (int k = 0; k < 2; ++k) dst[m][k] = *(const PG8_LAS bf16x8*)(lds + PG8_SA(b, h) + aoff + m * 2048 + k * 1024); } while (0)
; #define PG8_MMA(ai, bj, At, Bt) do { __builtin_amdgcn_s_setprio(1); _Pragma("unroll") for (int m = 0; m < 4; ++m) _Pragma("unroll") for (int n = 0; n < 2; ++n) _Pragma("unroll") for (int k = 0; k < 2; ++k) \
;         acc[ai][bj][m][n] = __builtin_amdgcn_mfma_f32_16x16x32_bf16(Bt[n][k], At[m][k], acc[ai][bj][m][n], 0, 0, 0); __builtin_amdgcn_s_setprio(0); } while (0)
; #define PG8_WAIT_V89() do { if constexpr (SLIVER) PG8_WAIT_V(9); else PG8_WAIT_V(8); } while (0)
; #define PG8_LDS_S(b) do { if constexpr (SLIVER) { Sf[0] = *(const PG8_LAS bf16x8*)(lds + STAGE_BYTES + (b) * 2048 + soff0); Sf[1] = *(const PG8_LAS bf16x8*)(lds + STAGE_BYTES + (b) * 2048 + (soff0 ^ 64)); } } while (0)
; #define PG8_WAIT_L(n) asm volatile("s_waitcnt lgkmcnt(" #n ")" ::: "memory")
; #define PG8_BAR __builtin_amdgcn_s_barrier()
; #define PG8_SCHED __builtin_amdgcn_sched_barrier(0)
; template <class Epi, class Sched, bool ALIGN_EPI = false, bool SP2 = false, bool SLIVER = false>
; __device__ __forceinline__ void gemm_phase(PG8_LAS unsigned char* lds, const Gemm g, const Sched& S, const Epi& E) {
;     ...
;             PG8_LDA(At, 0, 1); PG8_LDS_S(0); PG8_STAGE(PG8_SB(0, 0), b2, voffB); PG8_STAGE(PG8_SB(0, 1), b2 + hstep, voffB); PG8_STAGE(PG8_SA(0, 0), a2, voffA);
;             PG8_WAIT_V89(); PG8_WAIT_L(0); PG8_BAR; PG8_MMA(1, 0, At, B0); PG8_MMA(1, 1, At, B1); PG8_MMA_S(); PG8_BAR; PG8_SCHED;
	s_setprio 0
	s_add_i32 s68, 0, 0x20000
	v_lshl_add_u64 v[216:217], s[66:67], 0, v[198:199]
	s_add_i32 s66, s69, s18
	v_add_u32_e32 v74, s68, v221
	v_add_u32_e32 v75, s68, v222
	s_mov_b32 m0, s66
	ds_read_b128 v[66:69], v223 offset:16384
	ds_read_b128 v[70:73], v223 offset:17408
	ds_read_b128 v[224:227], v223 offset:18432
	ds_read_b128 v[228:231], v223 offset:19456
	ds_read_b128 v[232:235], v223 offset:20480
	ds_read_b128 v[240:243], v223 offset:21504
	ds_read_b128 v[244:247], v223 offset:22528
	ds_read_b128 v[248:251], v223 offset:23552
	ds_read_b128 v[166:169], v74
	ds_read_b128 v[170:173], v75
	global_load_lds_dwordx4 v[216:217], off
	v_lshl_add_u64 v[74:75], v[216:217], 0, s[64:65]
	s_add_i32 m0, s66, 0x2000
	s_add_i32 s13, s13, s18
	global_load_lds_dwordx4 v[74:75], off
	v_lshl_add_u64 v[74:75], v[216:217], 0, s[0:1]
	s_mov_b32 m0, s13
	v_lshl_add_u64 v[218:219], s[40:41], 0, v[196:197]
	global_load_lds_dwordx4 v[74:75], off
	v_lshl_add_u64 v[74:75], v[216:217], 0, s[74:75]
	s_add_i32 m0, s13, 0x2000
	s_nop 0
	global_load_lds_dwordx4 v[74:75], off
	s_mov_b32 m0, s19
	v_lshl_add_u64 v[74:75], v[218:219], 0, s[64:65]
	global_load_lds_dwordx4 v[218:219], off
	s_mov_b32 m0, s52
	s_nop 0
	global_load_lds_dwordx4 v[74:75], off
	s_waitcnt vmcnt(9)
	s_waitcnt lgkmcnt(0)
	s_setprio 1
	s_barrier
	v_mfma_f32_16x16x32_bf16 v[74:77], v[154:157], v[66:69], v[86:89]
	v_mfma_f32_16x16x32_bf16 v[78:81], v[162:165], v[66:69], v[82:85]
	v_mfma_f32_16x16x32_bf16 v[54:57], v[154:157], v[224:227], v[54:57]
	v_mfma_f32_16x16x32_bf16 v[50:53], v[162:165], v[224:227], v[50:53]
	v_mfma_f32_16x16x32_bf16 v[38:41], v[154:157], v[232:235], v[38:41]
	v_mfma_f32_16x16x32_bf16 v[34:37], v[162:165], v[232:235], v[34:37]
	v_mfma_f32_16x16x32_bf16 v[22:25], v[154:157], v[244:247], v[22:25]
	v_mfma_f32_16x16x32_bf16 v[18:21], v[162:165], v[244:247], v[18:21]
	v_mfma_f32_16x16x32_bf16 v[74:77], v[158:161], v[70:73], v[74:77]
	v_mfma_f32_16x16x32_bf16 v[78:81], v[174:177], v[70:73], v[78:81]
	v_mfma_f32_16x16x32_bf16 v[54:57], v[158:161], v[228:231], v[54:57]
	v_mfma_f32_16x16x32_bf16 v[50:53], v[174:177], v[228:231], v[50:53]
	v_mfma_f32_16x16x32_bf16 v[38:41], v[158:161], v[240:243], v[38:41]
	v_mfma_f32_16x16x32_bf16 v[34:37], v[174:177], v[240:243], v[34:37]
	v_mfma_f32_16x16x32_bf16 v[22:25], v[158:161], v[248:251], v[22:25]
	v_mfma_f32_16x16x32_bf16 v[18:21], v[174:177], v[248:251], v[18:21]
	s_setprio 0
	s_setprio 1
	v_mfma_f32_16x16x32_bf16 v[62:65], v[184:187], v[66:69], v[62:65]
	v_mfma_f32_16x16x32_bf16 v[62:65], v[188:191], v[70:73], v[62:65]
	v_mfma_f32_16x16x32_bf16 v[58:61], v[192:195], v[66:69], v[58:61]
	v_mfma_f32_16x16x32_bf16 v[58:61], v[180:183], v[70:73], v[58:61]
	v_mfma_f32_16x16x32_bf16 v[46:49], v[184:187], v[224:227], v[46:49]
	v_mfma_f32_16x16x32_bf16 v[46:49], v[188:191], v[228:231], v[46:49]
	v_mfma_f32_16x16x32_bf16 v[42:45], v[192:195], v[224:227], v[42:45]
	v_mfma_f32_16x16x32_bf16 v[42:45], v[180:183], v[228:231], v[42:45]
	v_mfma_f32_16x16x32_bf16 v[30:33], v[184:187], v[232:235], v[30:33]
	v_mfma_f32_16x16x32_bf16 v[30:33], v[188:191], v[240:243], v[30:33]
	v_mfma_f32_16x16x32_bf16 v[26:29], v[192:195], v[232:235], v[26:29]
	v_mfma_f32_16x16x32_bf16 v[26:29], v[180:183], v[240:243], v[26:29]
	v_mfma_f32_16x16x32_bf16 v[14:17], v[184:187], v[244:247], v[14:17]
	v_mfma_f32_16x16x32_bf16 v[14:17], v[188:191], v[248:251], v[14:17]
	v_mfma_f32_16x16x32_bf16 v[10:13], v[192:195], v[244:247], v[10:13]
	v_mfma_f32_16x16x32_bf16 v[10:13], v[180:183], v[248:251], v[10:13]
	s_setprio 0
	s_setprio 1
	s_and_b64 vcc, exec, s[82:83]
	s_cbranch_vccz .Lslv_b2
	v_mfma_f32_16x16x32_bf16 v[66:69], v[184:187], v[166:169], v[6:9]
	v_mfma_f32_16x16x32_bf16 v[70:73], v[192:195], v[166:169], v[2:5]
	v_mfma_f32_16x16x32_bf16 v[66:69], v[188:191], v[170:173], v[66:69]
	v_mfma_f32_16x16x32_bf16 v[70:73], v[180:183], v[170:173], v[70:73]
	s_branch .LBB0_815

; #define PG8_STAGE(bufoff, gbase, voff) do { _Pragma("unroll") for (int _i = 0; _i < 2; ++_i) \
;         __builtin_amdgcn_global_load_lds((const unsigned*)((const char*)(gbase) + (size_t)_i * qstep + (voff)[0]), (PG8_LAS unsigned*)(lds + (bufoff) + ldsw + _i * 8192), 16, 0, 0); } while (0)
; #define PG8_LDA(dst, b, h) do { _Pragma("unroll") for (int m = 0; m < 4; ++m) _Pragma("unroll") for (int k = 0; k < 2; ++k) dst[m][k] = *(const PG8_LAS bf16x8*)(lds + PG8_SA(b, h) + aoff + m * 2048 + k * 1024); } while (0)
; #define PG8_LDB(dst, b, h) do { _Pragma("unroll") for (int n = 0; n < 2; ++n) _Pragma("unroll") for (int k = 0; k < 2; ++k) dst[n][k] = *(const PG8_LAS bf16x8*)(lds + PG8_SB(b, h) + boff + n * 2048 + k * 1024); } while (0)
; #define PG8_MMA(ai, bj, At, Bt) do { __builtin_amdgcn_s_setprio(1); _Pragma("unroll") for (int m = 0; m < 4; ++m) _Pragma("unroll") for (int n = 0; n < 2; ++n) _Pragma("unroll") for (int k = 0; k < 2; ++k) \
;         acc[ai][bj][m][n] = __builtin_amdgcn_mfma_f32_16x16x32_bf16(Bt[n][k], At[m][k], acc[ai][bj][m][n], 0, 0, 0); __builtin_amdgcn_s_setprio(0); } while (0)
; #define PG8_WAIT_V89() do { if constexpr (SLIVER) PG8_WAIT_V(9); else PG8_WAIT_V(8); } while (0)
; #define PG8_WAIT_L(n) asm volatile("s_waitcnt lgkmcnt(" #n ")" ::: "memory")
; #define PG8_BAR __builtin_amdgcn_s_barrier()
; #define PG8_SCHED __builtin_amdgcn_sched_barrier(0)
; template <class Epi, class Sched, bool ALIGN_EPI = false, bool SP2 = false, bool SLIVER = false>
; __device__ __forceinline__ void gemm_phase(PG8_LAS unsigned char* lds, const Gemm g, const Sched& S, const Epi& E) {
;     ...
;             const bool last = (t == nt - 2);
;             const char* a1 = cA + (size_t)(t + 1) * kstep;
;             const char* a2 = last ? nA : cA + (size_t)(t + 2) * kstep; const char* b2 = last ? nB : cB + (size_t)(t + 2) * kstep;
;             const char* a3 = a2 + kstep; const char* b3 = b2 + kstep;
;             const char* s1 = cS + (size_t)(t + 1) * kstep; const char* s2 = last ? nS : cS + (size_t)(t + 2) * kstep;
;             if (last && has_next) S.a_ready(nxt);
;             if constexpr (SP2) {
;             PG8_LDB(B0, 0, 0); PG8_LDB(B1, 0, 1); PG8_SCHED; PG8_LDA(At, 0, 0); PG8_STAGE(PG8_SA(1, 1), a1 + hstep, voffA); PG8_STAGE_S(1, s1);
;             PG8_WAIT_V89(); PG8_WAIT_L(0); PG8_BAR; PG8_MMA(0, 0, At, B0); PG8_MMA(0, 1, At, B1); PG8_BAR; PG8_SCHED;
.LBB0_934:
	s_cmp_eq_u32 s66, s62
	s_cselect_b64 s[80:81], -1, 0
	s_add_u32 s12, s42, s62
	s_addc_u32 s13, s43, s63
	s_add_u32 s40, s12, 0x100
	s_addc_u32 s41, s13, 0
	s_and_b64 s[12:13], s[80:81], exec
	s_cselect_b32 s41, s95, s41
	s_cselect_b32 s40, s94, s40
	s_add_u32 s68, s17, s62
	s_addc_u32 s69, s45, s63
	s_add_i32 s76, 0, 0x10000
	s_and_b64 s[12:13], s[80:81], exec
	v_add_u32_e32 v138, s76, v212
	s_cselect_b32 s13, s97, s69
	s_cselect_b32 s12, s96, s68
	s_add_i32 s68, 0, 0x14000
	ds_read_b128 v[146:149], v138
	ds_read_b128 v[150:153], v138 offset:1024
	ds_read_b128 v[154:157], v138 offset:2048
	ds_read_b128 v[158:161], v138 offset:3072
	v_add_u32_e32 v138, s68, v212
	ds_read_b128 v[166:169], v138
	ds_read_b128 v[170:173], v138 offset:1024
	ds_read_b128 v[174:177], v138 offset:2048
	ds_read_b128 v[162:165], v138 offset:3072
	v_lshl_add_u64 v[202:203], v[198:199], 0, s[62:63]
	s_mov_b64 vcc, 0x90080
	v_lshl_add_u64 v[208:209], v[202:203], 0, vcc
	s_add_i32 m0, s93, 0xc000
	s_mov_b64 vcc, 0xd8080
	ds_read_b128 v[138:141], v215
	ds_read_b128 v[142:145], v215 offset:1024
	ds_read_b128 v[180:183], v215 offset:2048
	ds_read_b128 v[184:187], v215 offset:3072
	ds_read_b128 v[216:219], v215 offset:4096
	ds_read_b128 v[220:223], v215 offset:5120
	ds_read_b128 v[224:227], v215 offset:6144
	ds_read_b128 v[228:231], v215 offset:7168
	global_load_lds_dwordx4 v[208:209], off
	v_lshl_add_u64 v[202:203], v[202:203], 0, vcc
	s_add_i32 m0, s93, 0xe000
	s_nop 0
	global_load_lds_dwordx4 v[202:203], off
	v_lshl_add_u64 v[202:203], v[200:201], 0, s[62:63]
	s_add_i32 m0, s50, 0x20800
	s_nop 0
	global_load_lds_dword v[202:203], off
	s_waitcnt vmcnt(9)
	s_waitcnt lgkmcnt(0)
	s_setprio 1
	s_barrier
	v_mfma_f32_16x16x32_bf16 v[134:137], v[146:149], v[138:141], v[134:137]
	v_mfma_f32_16x16x32_bf16 v[134:137], v[150:153], v[142:145], v[134:137]
	v_mfma_f32_16x16x32_bf16 v[130:133], v[154:157], v[138:141], v[130:133]
	v_mfma_f32_16x16x32_bf16 v[130:133], v[158:161], v[142:145], v[130:133]
	v_mfma_f32_16x16x32_bf16 v[126:129], v[146:149], v[180:183], v[126:129]
	v_mfma_f32_16x16x32_bf16 v[126:129], v[150:153], v[184:187], v[126:129]
	v_mfma_f32_16x16x32_bf16 v[122:125], v[154:157], v[180:183], v[122:125]
	v_mfma_f32_16x16x32_bf16 v[122:125], v[158:161], v[184:187], v[122:125]
	v_mfma_f32_16x16x32_bf16 v[114:117], v[146:149], v[216:219], v[114:117]
	v_mfma_f32_16x16x32_bf16 v[114:117], v[150:153], v[220:223], v[114:117]
	v_mfma_f32_16x16x32_bf16 v[106:109], v[154:157], v[216:219], v[106:109]
	v_mfma_f32_16x16x32_bf16 v[106:109], v[158:161], v[220:223], v[106:109]
	v_mfma_f32_16x16x32_bf16 v[98:101], v[146:149], v[224:227], v[98:101]
	v_mfma_f32_16x16x32_bf16 v[98:101], v[150:153], v[228:231], v[98:101]
	v_mfma_f32_16x16x32_bf16 v[90:93], v[154:157], v[224:227], v[90:93]
	v_mfma_f32_16x16x32_bf16 v[90:93], v[158:161], v[228:231], v[90:93]
	s_setprio 0
	s_setprio 1
	v_mfma_f32_16x16x32_bf16 v[118:121], v[166:169], v[138:141], v[118:121]
	v_mfma_f32_16x16x32_bf16 v[118:121], v[170:173], v[142:145], v[118:121]
	v_mfma_f32_16x16x32_bf16 v[110:113], v[174:177], v[138:141], v[110:113]
	v_mfma_f32_16x16x32_bf16 v[110:113], v[162:165], v[142:145], v[110:113]
	v_mfma_f32_16x16x32_bf16 v[102:105], v[166:169], v[180:183], v[102:105]
	v_mfma_f32_16x16x32_bf16 v[102:105], v[170:173], v[184:187], v[102:105]
	v_mfma_f32_16x16x32_bf16 v[94:97], v[174:177], v[180:183], v[94:97]
	v_mfma_f32_16x16x32_bf16 v[94:97], v[162:165], v[184:187], v[94:97]
	v_mfma_f32_16x16x32_bf16 v[86:89], v[166:169], v[216:219], v[86:89]
	v_mfma_f32_16x16x32_bf16 v[86:89], v[170:173], v[220:223], v[86:89]
	v_mfma_f32_16x16x32_bf16 v[82:85], v[174:177], v[216:219], v[82:85]
	v_mfma_f32_16x16x32_bf16 v[82:85], v[162:165], v[220:223], v[82:85]
	v_mfma_f32_16x16x32_bf16 v[78:81], v[166:169], v[224:227], v[78:81]
	v_mfma_f32_16x16x32_bf16 v[78:81], v[170:173], v[228:231], v[78:81]
	v_mfma_f32_16x16x32_bf16 v[74:77], v[174:177], v[224:227], v[74:77]
	v_mfma_f32_16x16x32_bf16 v[74:77], v[162:165], v[228:231], v[74:77]
	s_barrier
; #define PG8_SB(B) __builtin_amdgcn_rcpf(1.f + expneg(B))
; #define PG8_SB(B) __builtin_amdgcn_rcpf(1.f + expneg(B))
; #define PG8_STAGE(bufoff, gbase, voff) do { _Pragma("unroll") for (int _i = 0; _i < 2; ++_i) \
;         __builtin_amdgcn_global_load_lds((const unsigned*)((const char*)(gbase) + (size_t)_i * qstep + (voff)[0]), (PG8_LAS unsigned*)(lds + (bufoff) + ldsw + _i * 8192), 16, 0, 0); } while (0)
; #define PG8_LDA(dst, b, h) do { _Pragma("unroll") for (int m = 0; m < 4; ++m) _Pragma("unroll") for (int k = 0; k < 2; ++k) dst[m][k] = *(const PG8_LAS bf16x8*)(lds + PG8_SA(b, h) + aoff + m * 2048 + k * 1024); } while (0)
; #define PG8_MMA(ai, bj, At, Bt) do { __builtin_amdgcn_s_setprio(1); _Pragma("unroll") for (int m = 0; m < 4; ++m) _Pragma("unroll") for (int n = 0; n < 2; ++n) _Pragma("unroll") for (int k = 0; k < 2; ++k) \
;         acc[ai][bj][m][n] = __builtin_amdgcn_mfma_f32_16x16x32_bf16(Bt[n][k], At[m][k], acc[ai][bj][m][n], 0, 0, 0); __builtin_amdgcn_s_setprio(0); } while (0)
; #define PG8_WAIT_V89() do { if constexpr (SLIVER) PG8_WAIT_V(9); else PG8_WAIT_V(8); } while (0)
; #define PG8_LDS_S(b) do { if constexpr (SLIVER) { Sf[0] = *(const PG8_LAS bf16x8*)(lds + STAGE_BYTES + (b) * 2048 + soff0); Sf[1] = *(const PG8_LAS bf16x8*)(lds + STAGE_BYTES + (b) * 2048 + (soff0 ^ 64)); } } while (0)
; #define PG8_WAIT_L(n) asm volatile("s_waitcnt lgkmcnt(" #n ")" ::: "memory")
; #define PG8_BAR __builtin_amdgcn_s_barrier()
; #define PG8_SCHED __builtin_amdgcn_sched_barrier(0)
; template <class Epi, class Sched, bool ALIGN_EPI = false, bool SP2 = false, bool SLIVER = false>
; __device__ __forceinline__ void gemm_phase(PG8_LAS unsigned char* lds, const Gemm g, const Sched& S, const Epi& E) {
;     ...
;             PG8_LDA(At, 0, 1); PG8_LDS_S(0); PG8_STAGE(PG8_SB(0, 0), b2, voffB); PG8_STAGE(PG8_SB(0, 1), b2 + hstep, voffB); PG8_STAGE(PG8_SA(0, 0), a2, voffA);
;             PG8_WAIT_V89(); PG8_WAIT_L(0); PG8_BAR; PG8_MMA(1, 0, At, B0); PG8_MMA(1, 1, At, B1); PG8_MMA_S(); PG8_BAR; PG8_SCHED;
	s_setprio 0
	s_add_i32 s69, 0, 0x20000
	v_lshl_add_u64 v[202:203], s[12:13], 0, v[190:191]
	s_add_i32 s12, s76, s92
	v_add_u32_e32 v178, s69, v213
	v_add_u32_e32 v184, s69, v214
	s_mov_b32 m0, s12
	ds_read_b128 v[138:141], v215 offset:16384
	ds_read_b128 v[142:145], v215 offset:17408
	ds_read_b128 v[216:219], v215 offset:18432
	ds_read_b128 v[220:223], v215 offset:19456
	ds_read_b128 v[224:227], v215 offset:20480
	ds_read_b128 v[228:231], v215 offset:21504
	ds_read_b128 v[232:235], v215 offset:22528
	ds_read_b128 v[240:243], v215 offset:23552
	ds_read_b128 v[180:183], v178
	ds_read_b128 v[184:187], v184
	global_load_lds_dwordx4 v[202:203], off
	v_lshl_add_u64 v[208:209], v[202:203], 0, s[70:71]
	s_add_i32 m0, s12, 0x2000
	s_add_i32 s12, s68, s92
	global_load_lds_dwordx4 v[208:209], off
	v_lshl_add_u64 v[208:209], v[202:203], 0, s[46:47]
	s_mov_b32 m0, s12
	v_lshl_add_u64 v[210:211], s[40:41], 0, v[188:189]
	global_load_lds_dwordx4 v[208:209], off
	v_lshl_add_u64 v[208:209], v[202:203], 0, s[6:7]
	s_add_i32 m0, s12, 0x2000
	s_nop 0
	global_load_lds_dwordx4 v[208:209], off
	s_mov_b32 m0, s93
	v_lshl_add_u64 v[208:209], v[210:211], 0, s[70:71]
	global_load_lds_dwordx4 v[210:211], off
	s_mov_b32 m0, s48
	s_nop 0
	global_load_lds_dwordx4 v[208:209], off
	s_waitcnt vmcnt(9)
	s_waitcnt lgkmcnt(0)
	s_setprio 1
	s_barrier
	v_mfma_f32_16x16x32_bf16 v[70:73], v[146:149], v[138:141], v[70:73]
	v_mfma_f32_16x16x32_bf16 v[70:73], v[150:153], v[142:145], v[70:73]
	v_mfma_f32_16x16x32_bf16 v[66:69], v[154:157], v[138:141], v[66:69]
	v_mfma_f32_16x16x32_bf16 v[66:69], v[158:161], v[142:145], v[66:69]
	v_mfma_f32_16x16x32_bf16 v[62:65], v[146:149], v[216:219], v[62:65]
	v_mfma_f32_16x16x32_bf16 v[62:65], v[150:153], v[220:223], v[62:65]
	v_mfma_f32_16x16x32_bf16 v[58:61], v[154:157], v[216:219], v[58:61]
	v_mfma_f32_16x16x32_bf16 v[58:61], v[158:161], v[220:223], v[58:61]
	v_mfma_f32_16x16x32_bf16 v[50:53], v[146:149], v[224:227], v[50:53]
	v_mfma_f32_16x16x32_bf16 v[50:53], v[150:153], v[228:231], v[50:53]
	v_mfma_f32_16x16x32_bf16 v[42:45], v[154:157], v[224:227], v[42:45]
	v_mfma_f32_16x16x32_bf16 v[42:45], v[158:161], v[228:231], v[42:45]
	v_mfma_f32_16x16x32_bf16 v[34:37], v[146:149], v[232:235], v[34:37]
	v_mfma_f32_16x16x32_bf16 v[34:37], v[150:153], v[240:243], v[34:37]
	v_mfma_f32_16x16x32_bf16 v[26:29], v[154:157], v[232:235], v[26:29]
	v_mfma_f32_16x16x32_bf16 v[26:29], v[158:161], v[240:243], v[26:29]
	s_setprio 0
	s_setprio 1
	v_mfma_f32_16x16x32_bf16 v[54:57], v[166:169], v[138:141], v[54:57]
	v_mfma_f32_16x16x32_bf16 v[54:57], v[170:173], v[142:145], v[54:57]
	v_mfma_f32_16x16x32_bf16 v[46:49], v[174:177], v[138:141], v[46:49]
	v_mfma_f32_16x16x32_bf16 v[46:49], v[162:165], v[142:145], v[46:49]
	v_mfma_f32_16x16x32_bf16 v[38:41], v[166:169], v[216:219], v[38:41]
	v_mfma_f32_16x16x32_bf16 v[38:41], v[170:173], v[220:223], v[38:41]
	v_mfma_f32_16x16x32_bf16 v[30:33], v[174:177], v[216:219], v[30:33]
	v_mfma_f32_16x16x32_bf16 v[30:33], v[162:165], v[220:223], v[30:33]
	v_mfma_f32_16x16x32_bf16 v[22:25], v[166:169], v[224:227], v[22:25]
	v_mfma_f32_16x16x32_bf16 v[22:25], v[170:173], v[228:231], v[22:25]
	v_mfma_f32_16x16x32_bf16 v[18:21], v[174:177], v[224:227], v[18:21]
	v_mfma_f32_16x16x32_bf16 v[18:21], v[162:165], v[228:231], v[18:21]
	v_mfma_f32_16x16x32_bf16 v[14:17], v[166:169], v[232:235], v[14:17]
	v_mfma_f32_16x16x32_bf16 v[14:17], v[170:173], v[240:243], v[14:17]
	v_mfma_f32_16x16x32_bf16 v[10:13], v[174:177], v[232:235], v[10:13]
	v_mfma_f32_16x16x32_bf16 v[10:13], v[162:165], v[240:243], v[10:13]
	s_setprio 0
	s_setprio 1
	s_and_b64 vcc, exec, s[90:91]
	s_cbranch_vccz .Lslv_b3
	v_mfma_f32_16x16x32_bf16 v[138:141], v[166:169], v[180:183], v[6:9]
	v_mfma_f32_16x16x32_bf16 v[142:145], v[174:177], v[180:183], v[2:5]
	v_mfma_f32_16x16x32_bf16 v[138:141], v[170:173], v[184:187], v[138:141]
	v_mfma_f32_16x16x32_bf16 v[142:145], v[162:165], v[184:187], v[142:145]
	s_branch .LBB0_938

; #define PG8_STAGE(bufoff, gbase, voff) do { _Pragma("unroll") for (int _i = 0; _i < 2; ++_i) \
;         __builtin_amdgcn_global_load_lds((const unsigned*)((const char*)(gbase) + (size_t)_i * qstep + (voff)[0]), (PG8_LAS unsigned*)(lds + (bufoff) + ldsw + _i * 8192), 16, 0, 0); } while (0)
; #define PG8_LDA(dst, b, h) do { _Pragma("unroll") for (int m = 0; m < 4; ++m) _Pragma("unroll") for (int k = 0; k < 2; ++k) dst[m][k] = *(const PG8_LAS bf16x8*)(lds + PG8_SA(b, h) + aoff + m * 2048 + k * 1024); } while (0)
; #define PG8_LDB(dst, b, h) do { _Pragma("unroll") for (int n = 0; n < 2; ++n) _Pragma("unroll") for (int k = 0; k < 2; ++k) dst[n][k] = *(const PG8_LAS bf16x8*)(lds + PG8_SB(b, h) + boff + n * 2048 + k * 1024); } while (0)
; #define PG8_MMA(ai, bj, At, Bt) do { __builtin_amdgcn_s_setprio(1); _Pragma("unroll") for (int m = 0; m < 4; ++m) _Pragma("unroll") for (int n = 0; n < 2; ++n) _Pragma("unroll") for (int k = 0; k < 2; ++k) \
;         acc[ai][bj][m][n] = __builtin_amdgcn_mfma_f32_16x16x32_bf16(Bt[n][k], At[m][k], acc[ai][bj][m][n], 0, 0, 0); __builtin_amdgcn_s_setprio(0); } while (0)
; #define PG8_WAIT_V89() do { if constexpr (SLIVER) PG8_WAIT_V(9); else PG8_WAIT_V(8); } while (0)
; #define PG8_STAGE_S(b, gbase) do { if constexpr (SLIVER) __builtin_amdgcn_global_load_lds((const unsigned*)((const char*)(gbase) + voffS), (PG8_LAS unsigned*)(lds + STAGE_BYTES + (b) * 2048 + wid * 256), 4, 0, 0); } while (0)
; #define PG8_WAIT_L(n) asm volatile("s_waitcnt lgkmcnt(" #n ")" ::: "memory")
; #define PG8_BAR __builtin_amdgcn_s_barrier()
; #define PG8_SCHED __builtin_amdgcn_sched_barrier(0)
; template <class Epi, class Sched, bool ALIGN_EPI = false, bool SP2 = false, bool SLIVER = false>
; __device__ __forceinline__ void gemm_phase(PG8_LAS unsigned char* lds, const Gemm g, const Sched& S, const Epi& E) {
;     ...
;             PG8_LDB(B0, 1, 0); PG8_LDB(B1, 1, 1); PG8_SCHED; PG8_LDA(At, 1, 0); PG8_STAGE(PG8_SA(0, 1), a2 + hstep, voffA); PG8_STAGE_S(0, s2);
;             PG8_WAIT_V89(); PG8_WAIT_L(0); PG8_BAR; PG8_MMA(0, 0, At, B0); PG8_MMA(0, 1, At, B1); PG8_BAR; PG8_SCHED;
.LBB0_938:
	s_barrier
	s_setprio 0
	s_add_u32 s12, s54, s62
	s_addc_u32 s13, s55, s63
	s_add_u32 s68, s12, 0x100
	s_addc_u32 s69, s13, 0
	s_and_b64 s[12:13], s[80:81], exec
	s_cselect_b32 s13, s19, s69
	s_cselect_b32 s12, s18, s68
	s_add_i32 s68, 0, 0x18000
	v_add_u32_e32 v2, s68, v212
	s_add_i32 s69, 0, 0x1c000
	ds_read_b128 v[146:149], v2
	ds_read_b128 v[150:153], v2 offset:1024
	ds_read_b128 v[154:157], v2 offset:2048
	ds_read_b128 v[158:161], v2 offset:3072
	v_add_u32_e32 v2, s69, v212
	ds_read_b128 v[166:169], v2
	ds_read_b128 v[170:173], v2 offset:1024
	ds_read_b128 v[174:177], v2 offset:2048
	ds_read_b128 v[162:165], v2 offset:3072
	s_mov_b32 m0, s49
	v_lshl_add_u64 v[208:209], v[210:211], 0, s[46:47]
	ds_read_b128 v[2:5], v215 offset:32768
	ds_read_b128 v[6:9], v215 offset:33792
	ds_read_b128 v[180:183], v215 offset:34816
	ds_read_b128 v[184:187], v215 offset:35840
	ds_read_b128 v[216:219], v215 offset:36864
	ds_read_b128 v[220:223], v215 offset:37888
	ds_read_b128 v[224:227], v215 offset:38912
	ds_read_b128 v[228:231], v215 offset:39936
	global_load_lds_dwordx4 v[208:209], off
	v_lshl_add_u64 v[208:209], v[210:211], 0, s[6:7]
	s_mov_b32 m0, s88
	s_nop 0
	global_load_lds_dwordx4 v[208:209], off
	v_lshl_add_u64 v[208:209], s[12:13], 0, v[192:193]
	s_mov_b32 m0, s89
	s_nop 0
	global_load_lds_dword v[208:209], off
	s_waitcnt vmcnt(9)
	s_waitcnt lgkmcnt(0)
	s_setprio 1
	s_barrier
	v_mfma_f32_16x16x32_bf16 v[134:137], v[146:149], v[2:5], v[134:137]
	v_mfma_f32_16x16x32_bf16 v[134:137], v[150:153], v[6:9], v[134:137]
	v_mfma_f32_16x16x32_bf16 v[130:133], v[154:157], v[2:5], v[130:133]
	v_mfma_f32_16x16x32_bf16 v[130:133], v[158:161], v[6:9], v[130:133]
	v_mfma_f32_16x16x32_bf16 v[126:129], v[146:149], v[180:183], v[126:129]
	v_mfma_f32_16x16x32_bf16 v[126:129], v[150:153], v[184:187], v[126:129]
	v_mfma_f32_16x16x32_bf16 v[122:125], v[154:157], v[180:183], v[122:125]
	v_mfma_f32_16x16x32_bf16 v[122:125], v[158:161], v[184:187], v[122:125]
	v_mfma_f32_16x16x32_bf16 v[114:117], v[146:149], v[216:219], v[114:117]
	v_mfma_f32_16x16x32_bf16 v[114:117], v[150:153], v[220:223], v[114:117]
	v_mfma_f32_16x16x32_bf16 v[106:109], v[154:157], v[216:219], v[106:109]
	v_mfma_f32_16x16x32_bf16 v[106:109], v[158:161], v[220:223], v[106:109]
	v_mfma_f32_16x16x32_bf16 v[98:101], v[146:149], v[224:227], v[98:101]
	v_mfma_f32_16x16x32_bf16 v[98:101], v[150:153], v[228:231], v[98:101]
	v_mfma_f32_16x16x32_bf16 v[90:93], v[154:157], v[224:227], v[90:93]
	v_mfma_f32_16x16x32_bf16 v[90:93], v[158:161], v[228:231], v[90:93]
	s_setprio 0
	s_setprio 1
	v_mfma_f32_16x16x32_bf16 v[118:121], v[166:169], v[2:5], v[118:121]
	v_mfma_f32_16x16x32_bf16 v[2:5], v[174:177], v[2:5], v[110:113]
	v_mfma_f32_16x16x32_bf16 v[110:113], v[162:165], v[6:9], v[2:5]
	v_mfma_f32_16x16x32_bf16 v[2:5], v[166:169], v[180:183], v[102:105]
	v_mfma_f32_16x16x32_bf16 v[102:105], v[170:173], v[184:187], v[2:5]
	v_mfma_f32_16x16x32_bf16 v[2:5], v[174:177], v[180:183], v[94:97]
	v_mfma_f32_16x16x32_bf16 v[94:97], v[162:165], v[184:187], v[2:5]
	v_mfma_f32_16x16x32_bf16 v[2:5], v[166:169], v[216:219], v[86:89]
	v_mfma_f32_16x16x32_bf16 v[86:89], v[170:173], v[220:223], v[2:5]
	v_mfma_f32_16x16x32_bf16 v[2:5], v[174:177], v[216:219], v[82:85]
	v_mfma_f32_16x16x32_bf16 v[82:85], v[162:165], v[220:223], v[2:5]
	v_mfma_f32_16x16x32_bf16 v[2:5], v[166:169], v[224:227], v[78:81]
	v_mfma_f32_16x16x32_bf16 v[78:81], v[170:173], v[228:231], v[2:5]
	v_mfma_f32_16x16x32_bf16 v[2:5], v[174:177], v[224:227], v[74:77]
	v_mfma_f32_16x16x32_bf16 v[118:121], v[170:173], v[6:9], v[118:121]
	v_mfma_f32_16x16x32_bf16 v[74:77], v[162:165], v[228:231], v[2:5]
	s_barrier
; #define PG8_SB(B) __builtin_amdgcn_rcpf(1.f + expneg(B))
; #define PG8_SB(B) __builtin_amdgcn_rcpf(1.f + expneg(B))
; #define PG8_STAGE(bufoff, gbase, voff) do { _Pragma("unroll") for (int _i = 0; _i < 2; ++_i) \
;         __builtin_amdgcn_global_load_lds((const unsigned*)((const char*)(gbase) + (size_t)_i * qstep + (voff)[0]), (PG8_LAS unsigned*)(lds + (bufoff) + ldsw + _i * 8192), 16, 0, 0); } while (0)
; #define PG8_LDA(dst, b, h) do { _Pragma("unroll") for (int m = 0; m < 4; ++m) _Pragma("unroll") for (int k = 0; k < 2; ++k) dst[m][k] = *(const PG8_LAS bf16x8*)(lds + PG8_SA(b, h) + aoff + m * 2048 + k * 1024); } while (0)
; #define PG8_MMA(ai, bj, At, Bt) do { __builtin_amdgcn_s_setprio(1); _Pragma("unroll") for (int m = 0; m < 4; ++m) _Pragma("unroll") for (int n = 0; n < 2; ++n) _Pragma("unroll") for (int k = 0; k < 2; ++k) \
;         acc[ai][bj][m][n] = __builtin_amdgcn_mfma_f32_16x16x32_bf16(Bt[n][k], At[m][k], acc[ai][bj][m][n], 0, 0, 0); __builtin_amdgcn_s_setprio(0); } while (0)
; #define PG8_WAIT_V89() do { if constexpr (SLIVER) PG8_WAIT_V(9); else PG8_WAIT_V(8); } while (0)
; #define PG8_LDS_S(b) do { if constexpr (SLIVER) { Sf[0] = *(const PG8_LAS bf16x8*)(lds + STAGE_BYTES + (b) * 2048 + soff0); Sf[1] = *(const PG8_LAS bf16x8*)(lds + STAGE_BYTES + (b) * 2048 + (soff0 ^ 64)); } } while (0)
; #define PG8_WAIT_L(n) asm volatile("s_waitcnt lgkmcnt(" #n ")" ::: "memory")
; #define PG8_BAR __builtin_amdgcn_s_barrier()
; #define PG8_SCHED __builtin_amdgcn_sched_barrier(0)
; template <class Epi, class Sched, bool ALIGN_EPI = false, bool SP2 = false, bool SLIVER = false>
; __device__ __forceinline__ void gemm_phase(PG8_LAS unsigned char* lds, const Gemm g, const Sched& S, const Epi& E) {
;     ...
;             PG8_LDA(At, 1, 1); PG8_LDS_S(1); PG8_STAGE(PG8_SB(1, 0), b3, voffB); PG8_STAGE(PG8_SB(1, 1), b3 + hstep, voffB); PG8_STAGE(PG8_SA(1, 0), a3, voffA);
;             PG8_WAIT_V89(); PG8_WAIT_L(0); PG8_BAR; PG8_MMA(1, 0, At, B0); PG8_MMA(1, 1, At, B1); PG8_MMA_S(); PG8_BAR; PG8_SCHED;
	s_setprio 0
	s_add_i32 s12, 0, 0x20800
	v_add_u32_e32 v178, s12, v213
	v_add_u32_e32 v184, s12, v214
	s_add_i32 s12, s68, s92
	v_lshl_add_u64 v[208:209], v[202:203], 0, s[26:27]
	s_mov_b32 m0, s12
	ds_read_b128 v[2:5], v215 offset:49152
	ds_read_b128 v[6:9], v215 offset:50176
	ds_read_b128 v[216:219], v215 offset:51200
	ds_read_b128 v[220:223], v215 offset:52224
	ds_read_b128 v[224:227], v215 offset:53248
	ds_read_b128 v[228:231], v215 offset:54272
	ds_read_b128 v[232:235], v215 offset:55296
	ds_read_b128 v[240:243], v215 offset:56320
	ds_read_b128 v[180:183], v178
	ds_read_b128 v[184:187], v184
	global_load_lds_dwordx4 v[208:209], off
	v_lshl_add_u64 v[208:209], v[202:203], 0, s[58:59]
	s_add_i32 m0, s12, 0x2000
	s_mov_b64 s[12:13], 0x90080
	global_load_lds_dwordx4 v[208:209], off
	v_lshl_add_u64 v[208:209], v[202:203], 0, s[12:13]
	s_add_i32 s12, s69, s92
	s_mov_b32 m0, s12
	s_mov_b64 s[68:69], 0xd8080
	global_load_lds_dwordx4 v[208:209], off
	v_lshl_add_u64 v[202:203], v[202:203], 0, s[68:69]
	s_add_i32 m0, s12, 0x2000
	s_nop 0
	global_load_lds_dwordx4 v[202:203], off
	v_lshl_add_u64 v[202:203], v[210:211], 0, s[26:27]
	s_mov_b32 m0, s51
	s_nop 0
	global_load_lds_dwordx4 v[202:203], off
	v_lshl_add_u64 v[202:203], v[210:211], 0, s[58:59]
	s_mov_b32 m0, s53
	s_nop 0
	global_load_lds_dwordx4 v[202:203], off
	s_waitcnt vmcnt(9)
	s_waitcnt lgkmcnt(0)
	s_setprio 1
	s_barrier
	v_mfma_f32_16x16x32_bf16 v[70:73], v[146:149], v[2:5], v[70:73]
	v_mfma_f32_16x16x32_bf16 v[70:73], v[150:153], v[6:9], v[70:73]
	v_mfma_f32_16x16x32_bf16 v[66:69], v[154:157], v[2:5], v[66:69]
	v_mfma_f32_16x16x32_bf16 v[66:69], v[158:161], v[6:9], v[66:69]
	v_mfma_f32_16x16x32_bf16 v[62:65], v[146:149], v[216:219], v[62:65]
	v_mfma_f32_16x16x32_bf16 v[62:65], v[150:153], v[220:223], v[62:65]
	v_mfma_f32_16x16x32_bf16 v[58:61], v[154:157], v[216:219], v[58:61]
	v_mfma_f32_16x16x32_bf16 v[58:61], v[158:161], v[220:223], v[58:61]
	v_mfma_f32_16x16x32_bf16 v[50:53], v[146:149], v[224:227], v[50:53]
	v_mfma_f32_16x16x32_bf16 v[50:53], v[150:153], v[228:231], v[50:53]
	v_mfma_f32_16x16x32_bf16 v[42:45], v[154:157], v[224:227], v[42:45]
	v_mfma_f32_16x16x32_bf16 v[42:45], v[158:161], v[228:231], v[42:45]
	v_mfma_f32_16x16x32_bf16 v[34:37], v[146:149], v[232:235], v[34:37]
	v_mfma_f32_16x16x32_bf16 v[34:37], v[150:153], v[240:243], v[34:37]
	v_mfma_f32_16x16x32_bf16 v[26:29], v[154:157], v[232:235], v[26:29]
	v_mfma_f32_16x16x32_bf16 v[26:29], v[158:161], v[240:243], v[26:29]
	s_setprio 0
	s_setprio 1
	v_mfma_f32_16x16x32_bf16 v[54:57], v[166:169], v[2:5], v[54:57]
	v_mfma_f32_16x16x32_bf16 v[2:5], v[174:177], v[2:5], v[46:49]
	v_mfma_f32_16x16x32_bf16 v[46:49], v[162:165], v[6:9], v[2:5]
	v_mfma_f32_16x16x32_bf16 v[2:5], v[166:169], v[216:219], v[38:41]
	v_mfma_f32_16x16x32_bf16 v[38:41], v[170:173], v[220:223], v[2:5]
	v_mfma_f32_16x16x32_bf16 v[2:5], v[174:177], v[216:219], v[30:33]
	v_mfma_f32_16x16x32_bf16 v[30:33], v[162:165], v[220:223], v[2:5]
	v_mfma_f32_16x16x32_bf16 v[2:5], v[166:169], v[224:227], v[22:25]
	v_mfma_f32_16x16x32_bf16 v[22:25], v[170:173], v[228:231], v[2:5]
	v_mfma_f32_16x16x32_bf16 v[2:5], v[174:177], v[224:227], v[18:21]
	v_mfma_f32_16x16x32_bf16 v[18:21], v[162:165], v[228:231], v[2:5]
	v_mfma_f32_16x16x32_bf16 v[2:5], v[166:169], v[232:235], v[14:17]
	v_mfma_f32_16x16x32_bf16 v[14:17], v[170:173], v[240:243], v[2:5]
	v_mfma_f32_16x16x32_bf16 v[2:5], v[174:177], v[232:235], v[10:13]
	v_mfma_f32_16x16x32_bf16 v[54:57], v[170:173], v[6:9], v[54:57]
	v_mfma_f32_16x16x32_bf16 v[10:13], v[162:165], v[240:243], v[2:5]
	s_setprio 0
	s_setprio 1
	s_and_b64 vcc, exec, s[90:91]
	s_cbranch_vccz .Lslv_c3
	v_mfma_f32_16x16x32_bf16 v[2:5], v[166:169], v[180:183], v[138:141]
	v_mfma_f32_16x16x32_bf16 v[6:9], v[170:173], v[184:187], v[2:5]
	v_mfma_f32_16x16x32_bf16 v[2:5], v[174:177], v[180:183], v[142:145]
	v_mfma_f32_16x16x32_bf16 v[2:5], v[162:165], v[184:187], v[2:5]
	s_branch .LBB0_933
